# speedup vs baseline: 1.0034x; 1.0034x over previous
; #define PG8_STAGE(bufoff, gbase, voff) do { _Pragma("unroll") for (int _i = 0; _i < 2; ++_i) \
;         __builtin_amdgcn_global_load_lds((const unsigned*)((const char*)(gbase) + (voff)[_i]), (PG8_LAS unsigned*)(lds + (bufoff) + ldsw + _i * 8192), 16, 0, 0); } while (0)
; #define PG8_LDA(dst, b, h) do { _Pragma("unroll") for (int m = 0; m < 4; ++m) _Pragma("unroll") for (int k = 0; k < 2; ++k) dst[m][k] = *(const PG8_LAS bf16x8*)(lds + PG8_SA(b, h) + aoff + m * 2048 + k * 1024); } while (0)
; #define PG8_LDB(dst, b, h) do { _Pragma("unroll") for (int n = 0; n < 2; ++n) _Pragma("unroll") for (int k = 0; k < 2; ++k) dst[n][k] = *(const PG8_LAS bf16x8*)(lds + PG8_SB(b, h) + boff + n * 2048 + k * 1024); } while (0)
; #define PG8_MMA(ai, bj, At, Bt) do { __builtin_amdgcn_s_setprio(1); _Pragma("unroll") for (int m = 0; m < 4; ++m) _Pragma("unroll") for (int n = 0; n < 2; ++n) _Pragma("unroll") for (int k = 0; k < 2; ++k) \
;         acc[ai][bj][m][n] = __builtin_amdgcn_mfma_f32_16x16x32_bf16(Bt[n][k], At[m][k], acc[ai][bj][m][n], 0, 0, 0); __builtin_amdgcn_s_setprio(0); } while (0)
; #define PG8_WAIT_V(n) asm volatile("s_waitcnt vmcnt(" #n ")" ::: "memory")
; #define PG8_WAIT_L(n) asm volatile("s_waitcnt lgkmcnt(" #n ")" ::: "memory")
; #define PG8_BAR __builtin_amdgcn_s_barrier()
; template <class Epi, class Sched, bool ALIGN_EPI = false, bool SP2 = false>
; __device__ __forceinline__ void gemm_phase(PG8_LAS unsigned char* lds, const Gemm g, const Sched& S, const Epi& E, const int wid_in) {
;     ...
;         for (int t = 0; t < nt; t += 2) {
;             const bool last = (t == nt - 2);
;             const char* a1 = cA + (size_t)(t + 1) * kstep;
;             const char* a2 = last ? nA : cA + (size_t)(t + 2) * kstep; const char* b2 = last ? nB : cB + (size_t)(t + 2) * kstep;
;             const char* a3 = a2 + kstep; const char* b3 = b2 + kstep;
;             if (last && has_next) S.a_ready(nxt);
;             if constexpr (SP2) {
;             PG8_LDB(B0, 0, 0); PG8_LDB(B1, 0, 1); PG8_SCHED; PG8_LDA(At, 0, 0); PG8_STAGE(PG8_SA(1, 1), a1 + hstep, voffA);
;             PG8_WAIT_V(8); PG8_WAIT_L(0); PG8_BAR; PG8_MMA(0, 0, At, B0); PG8_MMA(0, 1, At, B1); PG8_BAR; PG8_SCHED;
;             PG8_LDA(At, 0, 1); PG8_STAGE(PG8_SB(0, 0), b2, voffB); PG8_STAGE(PG8_SB(0, 1), b2 + hstep, voffB); PG8_STAGE(PG8_SA(0, 0), a2, voffA);
.LBB0_160:
	s_add_u32 s24, s42, 0xfff80080
	s_addc_u32 s25, s43, -1
	s_add_i32 s26, 0, 0x10000
	s_cmp_eq_u32 s39, 28
	s_cselect_b32 s47, s6, s25
	s_cselect_b32 s46, s7, s24
	v_add_u32_e32 v158, s26, v162
	s_cselect_b32 s45, s14, s35
	s_cselect_b32 s44, s15, s34
	s_add_i32 s27, 0, 0x14000
	ds_read_b128 v[146:149], v158
	ds_read_b128 v[150:153], v158 offset:1024
	ds_read_b128 v[154:157], v158 offset:2048
	ds_read_b128 v[164:167], v158 offset:3072
	v_add_u32_e32 v158, s27, v162
	ds_read_b128 v[168:171], v158
	ds_read_b128 v[172:175], v158 offset:1024
	ds_read_b128 v[176:179], v158 offset:2048
	ds_read_b128 v[186:189], v158 offset:3072
	v_lshl_add_u64 v[158:159], s[42:43], 0, v[142:143]
	s_add_i32 m0, s76, 0xc000
	ds_read_b128 v[190:193], v183
	ds_read_b128 v[194:197], v183 offset:1024
	ds_read_b128 v[198:201], v183 offset:2048
	ds_read_b128 v[202:205], v183 offset:3072
	ds_read_b128 v[206:209], v183 offset:4096
	ds_read_b128 v[210:213], v183 offset:5120
	ds_read_b128 v[214:217], v183 offset:6144
	ds_read_b128 v[218:221], v183 offset:7168
	global_load_lds_dwordx4 v[158:159], off
	v_lshl_add_u64 v[158:159], s[42:43], 0, v[144:145]
	s_add_i32 m0, s76, 0xe000
	s_nop 0
	global_load_lds_dwordx4 v[158:159], off
	s_waitcnt vmcnt(8)
	s_waitcnt lgkmcnt(0)
	s_barrier
	s_setprio 1
	s_waitcnt lgkmcnt(0)
	v_mfma_f32_16x16x32_bf16 v[124:127], v[146:149], v[190:193], v[124:127]
	v_mfma_f32_16x16x32_bf16 v[120:123], v[154:157], v[190:193], v[120:123]
	v_mfma_f32_16x16x32_bf16 v[108:111], v[146:149], v[198:201], v[108:111]
	v_mfma_f32_16x16x32_bf16 v[104:107], v[154:157], v[198:201], v[104:107]
	v_mfma_f32_16x16x32_bf16 v[92:95], v[146:149], v[206:209], v[92:95]
	v_mfma_f32_16x16x32_bf16 v[88:91], v[154:157], v[206:209], v[88:91]
	v_mfma_f32_16x16x32_bf16 v[76:79], v[146:149], v[214:217], v[76:79]
	v_mfma_f32_16x16x32_bf16 v[72:75], v[154:157], v[214:217], v[72:75]
	v_mfma_f32_16x16x32_bf16 v[124:127], v[150:153], v[194:197], v[124:127]
	v_mfma_f32_16x16x32_bf16 v[120:123], v[164:167], v[194:197], v[120:123]
	v_mfma_f32_16x16x32_bf16 v[108:111], v[150:153], v[202:205], v[108:111]
	v_mfma_f32_16x16x32_bf16 v[104:107], v[164:167], v[202:205], v[104:107]
	v_mfma_f32_16x16x32_bf16 v[92:95], v[150:153], v[210:213], v[92:95]
	v_mfma_f32_16x16x32_bf16 v[88:91], v[164:167], v[210:213], v[88:91]
	v_mfma_f32_16x16x32_bf16 v[76:79], v[150:153], v[218:221], v[76:79]
	v_mfma_f32_16x16x32_bf16 v[72:75], v[164:167], v[218:221], v[72:75]
	v_mfma_f32_16x16x32_bf16 v[116:119], v[168:171], v[190:193], v[116:119]
	v_mfma_f32_16x16x32_bf16 v[112:115], v[176:179], v[190:193], v[112:115]
	v_mfma_f32_16x16x32_bf16 v[100:103], v[168:171], v[198:201], v[100:103]
	v_mfma_f32_16x16x32_bf16 v[96:99], v[176:179], v[198:201], v[96:99]
	v_mfma_f32_16x16x32_bf16 v[84:87], v[168:171], v[206:209], v[84:87]
	v_mfma_f32_16x16x32_bf16 v[80:83], v[176:179], v[206:209], v[80:83]
	v_mfma_f32_16x16x32_bf16 v[68:71], v[168:171], v[214:217], v[68:71]
	v_mfma_f32_16x16x32_bf16 v[64:67], v[176:179], v[214:217], v[64:67]
	v_mfma_f32_16x16x32_bf16 v[116:119], v[172:175], v[194:197], v[116:119]
	v_mfma_f32_16x16x32_bf16 v[112:115], v[186:189], v[194:197], v[112:115]
	v_mfma_f32_16x16x32_bf16 v[100:103], v[172:175], v[202:205], v[100:103]
	v_mfma_f32_16x16x32_bf16 v[96:99], v[186:189], v[202:205], v[96:99]
	v_mfma_f32_16x16x32_bf16 v[84:87], v[172:175], v[210:213], v[84:87]
	v_mfma_f32_16x16x32_bf16 v[80:83], v[186:189], v[210:213], v[80:83]
	v_mfma_f32_16x16x32_bf16 v[68:71], v[172:175], v[218:221], v[68:71]
	v_mfma_f32_16x16x32_bf16 v[64:67], v[186:189], v[218:221], v[64:67]
	s_setprio 0
	s_barrier
	s_add_i32 s24, s26, s75
	v_lshl_add_u64 v[158:159], s[44:45], 0, v[130:131]
	s_mov_b32 m0, s24
	ds_read_b128 v[190:193], v183 offset:16384
	ds_read_b128 v[194:197], v183 offset:17408
	ds_read_b128 v[198:201], v183 offset:18432
	ds_read_b128 v[202:205], v183 offset:19456
	ds_read_b128 v[206:209], v183 offset:20480
	ds_read_b128 v[210:213], v183 offset:21504
	ds_read_b128 v[214:217], v183 offset:22528
	ds_read_b128 v[218:221], v183 offset:23552
	global_load_lds_dwordx4 v[158:159], off
	s_add_i32 m0, s24, 0x2000
	s_add_u32 s24, s44, 0x80000
	v_lshl_add_u64 v[180:181], s[44:45], 0, v[134:135]
	s_addc_u32 s25, s45, 0
	s_add_i32 s26, s27, s75
	global_load_lds_dwordx4 v[180:181], off
	v_lshl_add_u64 v[222:223], s[24:25], 0, v[130:131]
	s_mov_b32 m0, s26
	v_lshl_add_u64 v[224:225], s[46:47], 0, v[132:133]
	global_load_lds_dwordx4 v[222:223], off
	v_lshl_add_u64 v[222:223], s[24:25], 0, v[134:135]
	s_add_i32 m0, s26, 0x2000
	s_nop 0
	global_load_lds_dwordx4 v[222:223], off
	v_lshl_add_u64 v[222:223], s[46:47], 0, v[128:129]
	s_mov_b32 m0, s76
	s_nop 0
	global_load_lds_dwordx4 v[222:223], off
	s_mov_b32 m0, s77
	s_nop 0
	global_load_lds_dwordx4 v[224:225], off
	s_waitcnt vmcnt(8)
	s_waitcnt lgkmcnt(0)
	s_barrier
; #define PG8_STAGE(bufoff, gbase, voff) do { _Pragma("unroll") for (int _i = 0; _i < 2; ++_i) \
;         __builtin_amdgcn_global_load_lds((const unsigned*)((const char*)(gbase) + (voff)[_i]), (PG8_LAS unsigned*)(lds + (bufoff) + ldsw + _i * 8192), 16, 0, 0); } while (0)
; #define PG8_LDA(dst, b, h) do { _Pragma("unroll") for (int m = 0; m < 4; ++m) _Pragma("unroll") for (int k = 0; k < 2; ++k) dst[m][k] = *(const PG8_LAS bf16x8*)(lds + PG8_SA(b, h) + aoff + m * 2048 + k * 1024); } while (0)
; #define PG8_LDB(dst, b, h) do { _Pragma("unroll") for (int n = 0; n < 2; ++n) _Pragma("unroll") for (int k = 0; k < 2; ++k) dst[n][k] = *(const PG8_LAS bf16x8*)(lds + PG8_SB(b, h) + boff + n * 2048 + k * 1024); } while (0)
; #define PG8_MMA(ai, bj, At, Bt) do { __builtin_amdgcn_s_setprio(1); _Pragma("unroll") for (int m = 0; m < 4; ++m) _Pragma("unroll") for (int n = 0; n < 2; ++n) _Pragma("unroll") for (int k = 0; k < 2; ++k) \
;         acc[ai][bj][m][n] = __builtin_amdgcn_mfma_f32_16x16x32_bf16(Bt[n][k], At[m][k], acc[ai][bj][m][n], 0, 0, 0); __builtin_amdgcn_s_setprio(0); } while (0)
; #define PG8_WAIT_V(n) asm volatile("s_waitcnt vmcnt(" #n ")" ::: "memory")
; #define PG8_WAIT_L(n) asm volatile("s_waitcnt lgkmcnt(" #n ")" ::: "memory")
; #define PG8_BAR __builtin_amdgcn_s_barrier()
; #define PG8_SCHED __builtin_amdgcn_sched_barrier(0)
; template <class Epi, class Sched, bool ALIGN_EPI = false, bool SP2 = false>
; __device__ __forceinline__ void gemm_phase(PG8_LAS unsigned char* lds, const Gemm g, const Sched& S, const Epi& E, const int wid_in) {
;     ...
;             PG8_WAIT_V(8); PG8_WAIT_L(0); PG8_BAR; PG8_MMA(1, 0, At, B0); PG8_MMA(1, 1, At, B1); PG8_BAR; PG8_SCHED;
;             PG8_LDB(B0, 1, 0); PG8_LDB(B1, 1, 1); PG8_SCHED; PG8_LDA(At, 1, 0); PG8_STAGE(PG8_SA(0, 1), a2 + hstep, voffA);
;             PG8_WAIT_V(8); PG8_WAIT_L(0); PG8_BAR; PG8_MMA(0, 0, At, B0); PG8_MMA(0, 1, At, B1); PG8_BAR; PG8_SCHED;
	s_setprio 1
	s_waitcnt lgkmcnt(0)
	v_mfma_f32_16x16x32_bf16 v[60:63], v[146:149], v[190:193], v[60:63]
	v_mfma_f32_16x16x32_bf16 v[56:59], v[154:157], v[190:193], v[56:59]
	v_mfma_f32_16x16x32_bf16 v[44:47], v[146:149], v[198:201], v[44:47]
	v_mfma_f32_16x16x32_bf16 v[40:43], v[154:157], v[198:201], v[40:43]
	v_mfma_f32_16x16x32_bf16 v[28:31], v[146:149], v[206:209], v[28:31]
	v_mfma_f32_16x16x32_bf16 v[24:27], v[154:157], v[206:209], v[24:27]
	v_mfma_f32_16x16x32_bf16 v[12:15], v[146:149], v[214:217], v[12:15]
	v_mfma_f32_16x16x32_bf16 v[8:11], v[154:157], v[214:217], v[8:11]
	v_mfma_f32_16x16x32_bf16 v[60:63], v[150:153], v[194:197], v[60:63]
	v_mfma_f32_16x16x32_bf16 v[56:59], v[164:167], v[194:197], v[56:59]
	v_mfma_f32_16x16x32_bf16 v[44:47], v[150:153], v[202:205], v[44:47]
	v_mfma_f32_16x16x32_bf16 v[40:43], v[164:167], v[202:205], v[40:43]
	v_mfma_f32_16x16x32_bf16 v[28:31], v[150:153], v[210:213], v[28:31]
	v_mfma_f32_16x16x32_bf16 v[24:27], v[164:167], v[210:213], v[24:27]
	v_mfma_f32_16x16x32_bf16 v[12:15], v[150:153], v[218:221], v[12:15]
	v_mfma_f32_16x16x32_bf16 v[8:11], v[164:167], v[218:221], v[8:11]
	v_mfma_f32_16x16x32_bf16 v[52:55], v[168:171], v[190:193], v[52:55]
	v_mfma_f32_16x16x32_bf16 v[48:51], v[176:179], v[190:193], v[48:51]
	v_mfma_f32_16x16x32_bf16 v[36:39], v[168:171], v[198:201], v[36:39]
	v_mfma_f32_16x16x32_bf16 v[32:35], v[176:179], v[198:201], v[32:35]
	v_mfma_f32_16x16x32_bf16 v[20:23], v[168:171], v[206:209], v[20:23]
	v_mfma_f32_16x16x32_bf16 v[16:19], v[176:179], v[206:209], v[16:19]
	v_mfma_f32_16x16x32_bf16 v[4:7], v[168:171], v[214:217], v[4:7]
	v_mfma_f32_16x16x32_bf16 v[0:3], v[176:179], v[214:217], v[0:3]
	v_mfma_f32_16x16x32_bf16 v[52:55], v[172:175], v[194:197], v[52:55]
	v_mfma_f32_16x16x32_bf16 v[48:51], v[186:189], v[194:197], v[48:51]
	v_mfma_f32_16x16x32_bf16 v[36:39], v[172:175], v[202:205], v[36:39]
	v_mfma_f32_16x16x32_bf16 v[32:35], v[186:189], v[202:205], v[32:35]
	v_mfma_f32_16x16x32_bf16 v[20:23], v[172:175], v[210:213], v[20:23]
	v_mfma_f32_16x16x32_bf16 v[16:19], v[186:189], v[210:213], v[16:19]
	v_mfma_f32_16x16x32_bf16 v[4:7], v[172:175], v[218:221], v[4:7]
	v_mfma_f32_16x16x32_bf16 v[0:3], v[186:189], v[218:221], v[0:3]
	s_setprio 0
	s_barrier
	s_add_i32 s26, 0, 0x18000
	v_add_u32_e32 v160, s26, v162
	s_add_i32 s27, 0, 0x1c000
	ds_read_b128 v[146:149], v160
	ds_read_b128 v[150:153], v160 offset:1024
	ds_read_b128 v[154:157], v160 offset:2048
	ds_read_b128 v[164:167], v160 offset:3072
	v_add_u32_e32 v160, s27, v162
	ds_read_b128 v[168:171], v160
	ds_read_b128 v[172:175], v160 offset:1024
	ds_read_b128 v[176:179], v160 offset:2048
	ds_read_b128 v[186:189], v160 offset:3072
	s_add_u32 s24, s46, 0x80000
	s_addc_u32 s25, s47, 0
	s_mov_b32 m0, s78
	v_lshl_add_u64 v[226:227], s[24:25], 0, v[128:129]
	ds_read_b128 v[190:193], v183 offset:32768
	ds_read_b128 v[194:197], v183 offset:33792
	ds_read_b128 v[198:201], v183 offset:34816
	ds_read_b128 v[202:205], v183 offset:35840
	ds_read_b128 v[206:209], v183 offset:36864
	ds_read_b128 v[210:213], v183 offset:37888
	ds_read_b128 v[214:217], v183 offset:38912
	ds_read_b128 v[218:221], v183 offset:39936
	global_load_lds_dwordx4 v[226:227], off
	v_lshl_add_u64 v[226:227], s[24:25], 0, v[132:133]
	s_mov_b32 m0, s79
	s_nop 0
	global_load_lds_dwordx4 v[226:227], off
	s_waitcnt vmcnt(8)
	s_waitcnt lgkmcnt(0)
	s_barrier
	s_setprio 1
	s_waitcnt lgkmcnt(0)
	v_mfma_f32_16x16x32_bf16 v[124:127], v[146:149], v[190:193], v[124:127]
	v_mfma_f32_16x16x32_bf16 v[120:123], v[154:157], v[190:193], v[120:123]
	v_mfma_f32_16x16x32_bf16 v[108:111], v[146:149], v[198:201], v[108:111]
	v_mfma_f32_16x16x32_bf16 v[104:107], v[154:157], v[198:201], v[104:107]
	v_mfma_f32_16x16x32_bf16 v[92:95], v[146:149], v[206:209], v[92:95]
	v_mfma_f32_16x16x32_bf16 v[88:91], v[154:157], v[206:209], v[88:91]
	v_mfma_f32_16x16x32_bf16 v[76:79], v[146:149], v[214:217], v[76:79]
	v_mfma_f32_16x16x32_bf16 v[72:75], v[154:157], v[214:217], v[72:75]
	v_mfma_f32_16x16x32_bf16 v[124:127], v[150:153], v[194:197], v[124:127]
	v_mfma_f32_16x16x32_bf16 v[120:123], v[164:167], v[194:197], v[120:123]
	v_mfma_f32_16x16x32_bf16 v[108:111], v[150:153], v[202:205], v[108:111]
	v_mfma_f32_16x16x32_bf16 v[104:107], v[164:167], v[202:205], v[104:107]
	v_mfma_f32_16x16x32_bf16 v[92:95], v[150:153], v[210:213], v[92:95]
	v_mfma_f32_16x16x32_bf16 v[88:91], v[164:167], v[210:213], v[88:91]
	v_mfma_f32_16x16x32_bf16 v[76:79], v[150:153], v[218:221], v[76:79]
	v_mfma_f32_16x16x32_bf16 v[72:75], v[164:167], v[218:221], v[72:75]
	v_mfma_f32_16x16x32_bf16 v[116:119], v[168:171], v[190:193], v[116:119]
	v_mfma_f32_16x16x32_bf16 v[112:115], v[176:179], v[190:193], v[112:115]
	v_mfma_f32_16x16x32_bf16 v[100:103], v[168:171], v[198:201], v[100:103]
	v_mfma_f32_16x16x32_bf16 v[96:99], v[176:179], v[198:201], v[96:99]
	v_mfma_f32_16x16x32_bf16 v[84:87], v[168:171], v[206:209], v[84:87]
	v_mfma_f32_16x16x32_bf16 v[80:83], v[176:179], v[206:209], v[80:83]
	v_mfma_f32_16x16x32_bf16 v[68:71], v[168:171], v[214:217], v[68:71]
	v_mfma_f32_16x16x32_bf16 v[64:67], v[176:179], v[214:217], v[64:67]
	v_mfma_f32_16x16x32_bf16 v[116:119], v[172:175], v[194:197], v[116:119]
	v_mfma_f32_16x16x32_bf16 v[112:115], v[186:189], v[194:197], v[112:115]
	v_mfma_f32_16x16x32_bf16 v[100:103], v[172:175], v[202:205], v[100:103]
	v_mfma_f32_16x16x32_bf16 v[96:99], v[186:189], v[202:205], v[96:99]
	v_mfma_f32_16x16x32_bf16 v[84:87], v[172:175], v[210:213], v[84:87]
	v_mfma_f32_16x16x32_bf16 v[80:83], v[186:189], v[210:213], v[80:83]
	v_mfma_f32_16x16x32_bf16 v[68:71], v[172:175], v[218:221], v[68:71]
	v_mfma_f32_16x16x32_bf16 v[64:67], v[186:189], v[218:221], v[64:67]
	s_setprio 0
	s_barrier
; #define PG8_STAGE(bufoff, gbase, voff) do { _Pragma("unroll") for (int _i = 0; _i < 2; ++_i) \
;         __builtin_amdgcn_global_load_lds((const unsigned*)((const char*)(gbase) + (voff)[_i]), (PG8_LAS unsigned*)(lds + (bufoff) + ldsw + _i * 8192), 16, 0, 0); } while (0)
; #define PG8_LDA(dst, b, h) do { _Pragma("unroll") for (int m = 0; m < 4; ++m) _Pragma("unroll") for (int k = 0; k < 2; ++k) dst[m][k] = *(const PG8_LAS bf16x8*)(lds + PG8_SA(b, h) + aoff + m * 2048 + k * 1024); } while (0)
; #define PG8_MMA(ai, bj, At, Bt) do { __builtin_amdgcn_s_setprio(1); _Pragma("unroll") for (int m = 0; m < 4; ++m) _Pragma("unroll") for (int n = 0; n < 2; ++n) _Pragma("unroll") for (int k = 0; k < 2; ++k) \
;         acc[ai][bj][m][n] = __builtin_amdgcn_mfma_f32_16x16x32_bf16(Bt[n][k], At[m][k], acc[ai][bj][m][n], 0, 0, 0); __builtin_amdgcn_s_setprio(0); } while (0)
; #define PG8_WAIT_V(n) asm volatile("s_waitcnt vmcnt(" #n ")" ::: "memory")
; #define PG8_WAIT_L(n) asm volatile("s_waitcnt lgkmcnt(" #n ")" ::: "memory")
; #define PG8_BAR __builtin_amdgcn_s_barrier()
; #define PG8_SCHED __builtin_amdgcn_sched_barrier(0)
; template <class Epi, class Sched, bool ALIGN_EPI = false, bool SP2 = false>
; __device__ __forceinline__ void gemm_phase(PG8_LAS unsigned char* lds, const Gemm g, const Sched& S, const Epi& E, const int wid_in) {
;     ...
;             PG8_WAIT_V(8); PG8_WAIT_L(0); PG8_BAR; PG8_MMA(0, 0, At, B0); PG8_MMA(0, 1, At, B1); PG8_BAR; PG8_SCHED;
;             PG8_LDA(At, 1, 1); PG8_STAGE(PG8_SB(1, 0), b3, voffB); PG8_STAGE(PG8_SB(1, 1), b3 + hstep, voffB); PG8_STAGE(PG8_SA(1, 0), a3, voffA);
;             PG8_WAIT_V(8); PG8_WAIT_L(0); PG8_BAR; PG8_MMA(1, 0, At, B0); PG8_MMA(1, 1, At, B1); PG8_BAR; PG8_SCHED;
	s_add_i32 s24, s26, s75
	v_lshl_add_u64 v[158:159], v[158:159], 0, s[8:9]
	s_mov_b32 m0, s24
	ds_read_b128 v[190:193], v183 offset:49152
	ds_read_b128 v[194:197], v183 offset:50176
	ds_read_b128 v[198:201], v183 offset:51200
	ds_read_b128 v[202:205], v183 offset:52224
	ds_read_b128 v[206:209], v183 offset:53248
	ds_read_b128 v[210:213], v183 offset:54272
	ds_read_b128 v[214:217], v183 offset:55296
	ds_read_b128 v[218:221], v183 offset:56320
	global_load_lds_dwordx4 v[158:159], off
	s_add_i32 m0, s24, 0x2000
	s_add_u32 s24, s44, 0x80080
	v_lshl_add_u64 v[158:159], v[180:181], 0, s[8:9]
	s_addc_u32 s25, s45, 0
	s_add_i32 s26, s27, s75
	global_load_lds_dwordx4 v[158:159], off
	v_lshl_add_u64 v[158:159], s[24:25], 0, v[130:131]
	s_mov_b32 m0, s26
	s_nop 0
	global_load_lds_dwordx4 v[158:159], off
	v_lshl_add_u64 v[158:159], s[24:25], 0, v[134:135]
	s_add_i32 m0, s26, 0x2000
	s_nop 0
	global_load_lds_dwordx4 v[158:159], off
	v_lshl_add_u64 v[158:159], v[222:223], 0, s[8:9]
	s_mov_b32 m0, s81
	s_nop 0
	global_load_lds_dwordx4 v[158:159], off
	v_lshl_add_u64 v[158:159], v[224:225], 0, s[8:9]
	s_mov_b32 m0, s82
	s_nop 0
	global_load_lds_dwordx4 v[158:159], off
	s_waitcnt vmcnt(8)
	s_waitcnt lgkmcnt(0)
	s_barrier
	s_setprio 1
	s_waitcnt lgkmcnt(0)
	v_mfma_f32_16x16x32_bf16 v[60:63], v[146:149], v[190:193], v[60:63]
	v_mfma_f32_16x16x32_bf16 v[56:59], v[154:157], v[190:193], v[56:59]
	v_mfma_f32_16x16x32_bf16 v[44:47], v[146:149], v[198:201], v[44:47]
	v_mfma_f32_16x16x32_bf16 v[40:43], v[154:157], v[198:201], v[40:43]
	v_mfma_f32_16x16x32_bf16 v[28:31], v[146:149], v[206:209], v[28:31]
	v_mfma_f32_16x16x32_bf16 v[24:27], v[154:157], v[206:209], v[24:27]
	v_mfma_f32_16x16x32_bf16 v[12:15], v[146:149], v[214:217], v[12:15]
	v_mfma_f32_16x16x32_bf16 v[8:11], v[154:157], v[214:217], v[8:11]
	v_mfma_f32_16x16x32_bf16 v[60:63], v[150:153], v[194:197], v[60:63]
	v_mfma_f32_16x16x32_bf16 v[56:59], v[164:167], v[194:197], v[56:59]
	v_mfma_f32_16x16x32_bf16 v[44:47], v[150:153], v[202:205], v[44:47]
	v_mfma_f32_16x16x32_bf16 v[40:43], v[164:167], v[202:205], v[40:43]
	v_mfma_f32_16x16x32_bf16 v[28:31], v[150:153], v[210:213], v[28:31]
	v_mfma_f32_16x16x32_bf16 v[24:27], v[164:167], v[210:213], v[24:27]
	v_mfma_f32_16x16x32_bf16 v[12:15], v[150:153], v[218:221], v[12:15]
	v_mfma_f32_16x16x32_bf16 v[8:11], v[164:167], v[218:221], v[8:11]
	v_mfma_f32_16x16x32_bf16 v[52:55], v[168:171], v[190:193], v[52:55]
	v_mfma_f32_16x16x32_bf16 v[48:51], v[176:179], v[190:193], v[48:51]
	v_mfma_f32_16x16x32_bf16 v[36:39], v[168:171], v[198:201], v[36:39]
	v_mfma_f32_16x16x32_bf16 v[32:35], v[176:179], v[198:201], v[32:35]
	v_mfma_f32_16x16x32_bf16 v[20:23], v[168:171], v[206:209], v[20:23]
	v_mfma_f32_16x16x32_bf16 v[16:19], v[176:179], v[206:209], v[16:19]
	v_mfma_f32_16x16x32_bf16 v[4:7], v[168:171], v[214:217], v[4:7]
	v_mfma_f32_16x16x32_bf16 v[0:3], v[176:179], v[214:217], v[0:3]
	v_mfma_f32_16x16x32_bf16 v[52:55], v[172:175], v[194:197], v[52:55]
	v_mfma_f32_16x16x32_bf16 v[48:51], v[186:189], v[194:197], v[48:51]
	v_mfma_f32_16x16x32_bf16 v[36:39], v[172:175], v[202:205], v[36:39]
	v_mfma_f32_16x16x32_bf16 v[32:35], v[186:189], v[202:205], v[32:35]
	v_mfma_f32_16x16x32_bf16 v[20:23], v[172:175], v[210:213], v[20:23]
	v_mfma_f32_16x16x32_bf16 v[16:19], v[186:189], v[210:213], v[16:19]
	v_mfma_f32_16x16x32_bf16 v[4:7], v[172:175], v[218:221], v[4:7]
	v_mfma_f32_16x16x32_bf16 v[0:3], v[186:189], v[218:221], v[0:3]
	s_setprio 0
	s_barrier
	s_add_i32 s39, s39, 2
	s_add_u32 s42, s42, 0x100
	s_addc_u32 s43, s43, 0
	s_add_u32 s34, s34, 0x100
	s_addc_u32 s35, s35, 0
	s_cmp_gt_u32 s39, 29
	s_cbranch_scc0 .LBB0_160
	s_and_b64 vcc, exec, s[60:61]
	s_movk_i32 s26, 0x2000
	s_cbranch_vccz .LBB0_163
	s_barrier

; #define PG8_STAGE(bufoff, gbase, voff) do { _Pragma("unroll") for (int _i = 0; _i < 2; ++_i) \
;         __builtin_amdgcn_global_load_lds((const unsigned*)((const char*)(gbase) + (voff)[_i]), (PG8_LAS unsigned*)(lds + (bufoff) + ldsw + _i * 8192), 16, 0, 0); } while (0)
; #define PG8_LDA(dst, b, h) do { _Pragma("unroll") for (int m = 0; m < 4; ++m) _Pragma("unroll") for (int k = 0; k < 2; ++k) dst[m][k] = *(const PG8_LAS bf16x8*)(lds + PG8_SA(b, h) + aoff + m * 2048 + k * 1024); } while (0)
; #define PG8_LDB(dst, b, h) do { _Pragma("unroll") for (int n = 0; n < 2; ++n) _Pragma("unroll") for (int k = 0; k < 2; ++k) dst[n][k] = *(const PG8_LAS bf16x8*)(lds + PG8_SB(b, h) + boff + n * 2048 + k * 1024); } while (0)
; #define PG8_MMA(ai, bj, At, Bt) do { __builtin_amdgcn_s_setprio(1); _Pragma("unroll") for (int m = 0; m < 4; ++m) _Pragma("unroll") for (int n = 0; n < 2; ++n) _Pragma("unroll") for (int k = 0; k < 2; ++k) \
;         acc[ai][bj][m][n] = __builtin_amdgcn_mfma_f32_16x16x32_bf16(Bt[n][k], At[m][k], acc[ai][bj][m][n], 0, 0, 0); __builtin_amdgcn_s_setprio(0); } while (0)
; #define PG8_WAIT_V(n) asm volatile("s_waitcnt vmcnt(" #n ")" ::: "memory")
; #define PG8_WAIT_L(n) asm volatile("s_waitcnt lgkmcnt(" #n ")" ::: "memory")
; #define PG8_BAR __builtin_amdgcn_s_barrier()
; template <class Epi, class Sched, bool ALIGN_EPI = false, bool SP2 = false>
; __device__ __forceinline__ void gemm_phase(PG8_LAS unsigned char* lds, const Gemm g, const Sched& S, const Epi& E, const int wid_in) {
;     ...
;         for (int t = 0; t < nt; t += 2) {
;             const bool last = (t == nt - 2);
;             const char* a1 = cA + (size_t)(t + 1) * kstep;
;             const char* a2 = last ? nA : cA + (size_t)(t + 2) * kstep; const char* b2 = last ? nB : cB + (size_t)(t + 2) * kstep;
;             const char* a3 = a2 + kstep; const char* b3 = b2 + kstep;
;             if (last && has_next) S.a_ready(nxt);
;             if constexpr (SP2) {
;             PG8_LDB(B0, 0, 0); PG8_LDB(B1, 0, 1); PG8_SCHED; PG8_LDA(At, 0, 0); PG8_STAGE(PG8_SA(1, 1), a1 + hstep, voffA);
;             PG8_WAIT_V(8); PG8_WAIT_L(0); PG8_BAR; PG8_MMA(0, 0, At, B0); PG8_MMA(0, 1, At, B1); PG8_BAR; PG8_SCHED;
;             PG8_LDA(At, 0, 1); PG8_STAGE(PG8_SB(0, 0), b2, voffB); PG8_STAGE(PG8_SB(0, 1), b2 + hstep, voffB); PG8_STAGE(PG8_SA(0, 0), a2, voffA);
.LBB0_527:
	s_add_u32 s24, s54, 0xfffc0080
	s_addc_u32 s25, s55, -1
	s_add_i32 s26, 0, 0x10000
	s_cmp_eq_u32 s71, 12
	s_cselect_b32 s59, s14, s25
	s_cselect_b32 s58, s15, s24
	v_add_u32_e32 v142, s26, v145
	s_cselect_b32 s57, s45, s70
	s_cselect_b32 s56, s47, s69
	s_add_i32 s27, 0, 0x14000
	ds_read_b128 v[138:141], v142
	ds_read_b128 v[148:151], v142 offset:1024
	ds_read_b128 v[152:155], v142 offset:2048
	ds_read_b128 v[156:159], v142 offset:3072
	v_add_u32_e32 v142, s27, v145
	ds_read_b128 v[162:165], v142
	ds_read_b128 v[166:169], v142 offset:1024
	ds_read_b128 v[170:173], v142 offset:2048
	ds_read_b128 v[174:177], v142 offset:3072
	v_lshl_add_u64 v[142:143], s[54:55], 0, v[134:135]
	s_add_i32 m0, s53, 0xc000
	ds_read_b128 v[178:181], v147
	ds_read_b128 v[182:185], v147 offset:1024
	ds_read_b128 v[186:189], v147 offset:2048
	ds_read_b128 v[190:193], v147 offset:3072
	ds_read_b128 v[194:197], v147 offset:4096
	ds_read_b128 v[198:201], v147 offset:5120
	ds_read_b128 v[202:205], v147 offset:6144
	ds_read_b128 v[206:209], v147 offset:7168
	global_load_lds_dwordx4 v[142:143], off
	v_lshl_add_u64 v[142:143], s[54:55], 0, v[136:137]
	s_add_i32 m0, s53, 0xe000
	s_nop 0
	global_load_lds_dwordx4 v[142:143], off
	s_waitcnt vmcnt(8)
	s_waitcnt lgkmcnt(0)
	s_barrier
	s_setprio 1
	s_waitcnt lgkmcnt(0)
	v_mfma_f32_16x16x32_bf16 v[124:127], v[138:141], v[178:181], v[124:127]
	v_mfma_f32_16x16x32_bf16 v[120:123], v[152:155], v[178:181], v[120:123]
	v_mfma_f32_16x16x32_bf16 v[108:111], v[138:141], v[186:189], v[108:111]
	v_mfma_f32_16x16x32_bf16 v[104:107], v[152:155], v[186:189], v[104:107]
	v_mfma_f32_16x16x32_bf16 v[92:95], v[138:141], v[194:197], v[92:95]
	v_mfma_f32_16x16x32_bf16 v[88:91], v[152:155], v[194:197], v[88:91]
	v_mfma_f32_16x16x32_bf16 v[76:79], v[138:141], v[202:205], v[76:79]
	v_mfma_f32_16x16x32_bf16 v[72:75], v[152:155], v[202:205], v[72:75]
	v_mfma_f32_16x16x32_bf16 v[124:127], v[148:151], v[182:185], v[124:127]
	v_mfma_f32_16x16x32_bf16 v[120:123], v[156:159], v[182:185], v[120:123]
	v_mfma_f32_16x16x32_bf16 v[108:111], v[148:151], v[190:193], v[108:111]
	v_mfma_f32_16x16x32_bf16 v[104:107], v[156:159], v[190:193], v[104:107]
	v_mfma_f32_16x16x32_bf16 v[92:95], v[148:151], v[198:201], v[92:95]
	v_mfma_f32_16x16x32_bf16 v[88:91], v[156:159], v[198:201], v[88:91]
	v_mfma_f32_16x16x32_bf16 v[76:79], v[148:151], v[206:209], v[76:79]
	v_mfma_f32_16x16x32_bf16 v[72:75], v[156:159], v[206:209], v[72:75]
	v_mfma_f32_16x16x32_bf16 v[116:119], v[162:165], v[178:181], v[116:119]
	v_mfma_f32_16x16x32_bf16 v[112:115], v[170:173], v[178:181], v[112:115]
	v_mfma_f32_16x16x32_bf16 v[100:103], v[162:165], v[186:189], v[100:103]
	v_mfma_f32_16x16x32_bf16 v[96:99], v[170:173], v[186:189], v[96:99]
	v_mfma_f32_16x16x32_bf16 v[84:87], v[162:165], v[194:197], v[84:87]
	v_mfma_f32_16x16x32_bf16 v[80:83], v[170:173], v[194:197], v[80:83]
	v_mfma_f32_16x16x32_bf16 v[68:71], v[162:165], v[202:205], v[68:71]
	v_mfma_f32_16x16x32_bf16 v[64:67], v[170:173], v[202:205], v[64:67]
	v_mfma_f32_16x16x32_bf16 v[116:119], v[166:169], v[182:185], v[116:119]
	v_mfma_f32_16x16x32_bf16 v[112:115], v[174:177], v[182:185], v[112:115]
	v_mfma_f32_16x16x32_bf16 v[100:103], v[166:169], v[190:193], v[100:103]
	v_mfma_f32_16x16x32_bf16 v[96:99], v[174:177], v[190:193], v[96:99]
	v_mfma_f32_16x16x32_bf16 v[84:87], v[166:169], v[198:201], v[84:87]
	v_mfma_f32_16x16x32_bf16 v[80:83], v[174:177], v[198:201], v[80:83]
	v_mfma_f32_16x16x32_bf16 v[68:71], v[166:169], v[206:209], v[68:71]
	v_mfma_f32_16x16x32_bf16 v[64:67], v[174:177], v[206:209], v[64:67]
	s_setprio 0
	s_barrier
	s_add_i32 s24, s26, s62
	v_lshl_add_u64 v[142:143], s[56:57], 0, v[160:161]
	s_mov_b32 m0, s24
	ds_read_b128 v[178:181], v147 offset:16384
	ds_read_b128 v[182:185], v147 offset:17408
	ds_read_b128 v[186:189], v147 offset:18432
	ds_read_b128 v[190:193], v147 offset:19456
	ds_read_b128 v[194:197], v147 offset:20480
	ds_read_b128 v[198:201], v147 offset:21504
	ds_read_b128 v[202:205], v147 offset:22528
	ds_read_b128 v[206:209], v147 offset:23552
	global_load_lds_dwordx4 v[142:143], off
	s_add_i32 m0, s24, 0x2000
	s_add_u32 s24, s56, 0x40000
	v_lshl_add_u64 v[210:211], s[56:57], 0, v[132:133]
	s_addc_u32 s25, s57, 0
	s_add_i32 s26, s27, s62
	global_load_lds_dwordx4 v[210:211], off
	v_lshl_add_u64 v[212:213], s[24:25], 0, v[160:161]
	s_mov_b32 m0, s26
	v_lshl_add_u64 v[214:215], s[58:59], 0, v[130:131]
	global_load_lds_dwordx4 v[212:213], off
	v_lshl_add_u64 v[212:213], s[24:25], 0, v[132:133]
	s_add_i32 m0, s26, 0x2000
	s_nop 0
	global_load_lds_dwordx4 v[212:213], off
	v_lshl_add_u64 v[212:213], s[58:59], 0, v[128:129]
	s_mov_b32 m0, s53
	s_nop 0
	global_load_lds_dwordx4 v[212:213], off
	s_mov_b32 m0, s63
	s_nop 0
	global_load_lds_dwordx4 v[214:215], off
	s_waitcnt vmcnt(8)
	s_waitcnt lgkmcnt(0)
	s_barrier
; #define PG8_STAGE(bufoff, gbase, voff) do { _Pragma("unroll") for (int _i = 0; _i < 2; ++_i) \
;         __builtin_amdgcn_global_load_lds((const unsigned*)((const char*)(gbase) + (voff)[_i]), (PG8_LAS unsigned*)(lds + (bufoff) + ldsw + _i * 8192), 16, 0, 0); } while (0)
; #define PG8_LDA(dst, b, h) do { _Pragma("unroll") for (int m = 0; m < 4; ++m) _Pragma("unroll") for (int k = 0; k < 2; ++k) dst[m][k] = *(const PG8_LAS bf16x8*)(lds + PG8_SA(b, h) + aoff + m * 2048 + k * 1024); } while (0)
; #define PG8_LDB(dst, b, h) do { _Pragma("unroll") for (int n = 0; n < 2; ++n) _Pragma("unroll") for (int k = 0; k < 2; ++k) dst[n][k] = *(const PG8_LAS bf16x8*)(lds + PG8_SB(b, h) + boff + n * 2048 + k * 1024); } while (0)
; #define PG8_MMA(ai, bj, At, Bt) do { __builtin_amdgcn_s_setprio(1); _Pragma("unroll") for (int m = 0; m < 4; ++m) _Pragma("unroll") for (int n = 0; n < 2; ++n) _Pragma("unroll") for (int k = 0; k < 2; ++k) \
;         acc[ai][bj][m][n] = __builtin_amdgcn_mfma_f32_16x16x32_bf16(Bt[n][k], At[m][k], acc[ai][bj][m][n], 0, 0, 0); __builtin_amdgcn_s_setprio(0); } while (0)
; #define PG8_WAIT_V(n) asm volatile("s_waitcnt vmcnt(" #n ")" ::: "memory")
; #define PG8_WAIT_L(n) asm volatile("s_waitcnt lgkmcnt(" #n ")" ::: "memory")
; #define PG8_BAR __builtin_amdgcn_s_barrier()
; #define PG8_SCHED __builtin_amdgcn_sched_barrier(0)
; template <class Epi, class Sched, bool ALIGN_EPI = false, bool SP2 = false>
; __device__ __forceinline__ void gemm_phase(PG8_LAS unsigned char* lds, const Gemm g, const Sched& S, const Epi& E, const int wid_in) {
;     ...
;             PG8_WAIT_V(8); PG8_WAIT_L(0); PG8_BAR; PG8_MMA(1, 0, At, B0); PG8_MMA(1, 1, At, B1); PG8_BAR; PG8_SCHED;
;             PG8_LDB(B0, 1, 0); PG8_LDB(B1, 1, 1); PG8_SCHED; PG8_LDA(At, 1, 0); PG8_STAGE(PG8_SA(0, 1), a2 + hstep, voffA);
;             PG8_WAIT_V(8); PG8_WAIT_L(0); PG8_BAR; PG8_MMA(0, 0, At, B0); PG8_MMA(0, 1, At, B1); PG8_BAR; PG8_SCHED;
	s_setprio 1
	s_waitcnt lgkmcnt(0)
	v_mfma_f32_16x16x32_bf16 v[60:63], v[138:141], v[178:181], v[60:63]
	v_mfma_f32_16x16x32_bf16 v[56:59], v[152:155], v[178:181], v[56:59]
	v_mfma_f32_16x16x32_bf16 v[44:47], v[138:141], v[186:189], v[44:47]
	v_mfma_f32_16x16x32_bf16 v[40:43], v[152:155], v[186:189], v[40:43]
	v_mfma_f32_16x16x32_bf16 v[28:31], v[138:141], v[194:197], v[28:31]
	v_mfma_f32_16x16x32_bf16 v[24:27], v[152:155], v[194:197], v[24:27]
	v_mfma_f32_16x16x32_bf16 v[12:15], v[138:141], v[202:205], v[12:15]
	v_mfma_f32_16x16x32_bf16 v[8:11], v[152:155], v[202:205], v[8:11]
	v_mfma_f32_16x16x32_bf16 v[60:63], v[148:151], v[182:185], v[60:63]
	v_mfma_f32_16x16x32_bf16 v[56:59], v[156:159], v[182:185], v[56:59]
	v_mfma_f32_16x16x32_bf16 v[44:47], v[148:151], v[190:193], v[44:47]
	v_mfma_f32_16x16x32_bf16 v[40:43], v[156:159], v[190:193], v[40:43]
	v_mfma_f32_16x16x32_bf16 v[28:31], v[148:151], v[198:201], v[28:31]
	v_mfma_f32_16x16x32_bf16 v[24:27], v[156:159], v[198:201], v[24:27]
	v_mfma_f32_16x16x32_bf16 v[12:15], v[148:151], v[206:209], v[12:15]
	v_mfma_f32_16x16x32_bf16 v[8:11], v[156:159], v[206:209], v[8:11]
	v_mfma_f32_16x16x32_bf16 v[52:55], v[162:165], v[178:181], v[52:55]
	v_mfma_f32_16x16x32_bf16 v[48:51], v[170:173], v[178:181], v[48:51]
	v_mfma_f32_16x16x32_bf16 v[36:39], v[162:165], v[186:189], v[36:39]
	v_mfma_f32_16x16x32_bf16 v[32:35], v[170:173], v[186:189], v[32:35]
	v_mfma_f32_16x16x32_bf16 v[20:23], v[162:165], v[194:197], v[20:23]
	v_mfma_f32_16x16x32_bf16 v[16:19], v[170:173], v[194:197], v[16:19]
	v_mfma_f32_16x16x32_bf16 v[4:7], v[162:165], v[202:205], v[4:7]
	v_mfma_f32_16x16x32_bf16 v[0:3], v[170:173], v[202:205], v[0:3]
	v_mfma_f32_16x16x32_bf16 v[52:55], v[166:169], v[182:185], v[52:55]
	v_mfma_f32_16x16x32_bf16 v[48:51], v[174:177], v[182:185], v[48:51]
	v_mfma_f32_16x16x32_bf16 v[36:39], v[166:169], v[190:193], v[36:39]
	v_mfma_f32_16x16x32_bf16 v[32:35], v[174:177], v[190:193], v[32:35]
	v_mfma_f32_16x16x32_bf16 v[20:23], v[166:169], v[198:201], v[20:23]
	v_mfma_f32_16x16x32_bf16 v[16:19], v[174:177], v[198:201], v[16:19]
	v_mfma_f32_16x16x32_bf16 v[4:7], v[166:169], v[206:209], v[4:7]
	v_mfma_f32_16x16x32_bf16 v[0:3], v[174:177], v[206:209], v[0:3]
	s_setprio 0
	s_barrier
	s_add_i32 s26, 0, 0x18000
	s_add_i32 s27, 0, 0x1c000
	v_add_u32_e32 v156, s26, v145
	v_add_u32_e32 v174, s27, v145
	ds_read_b128 v[138:141], v156
	ds_read_b128 v[148:151], v156 offset:1024
	ds_read_b128 v[152:155], v156 offset:2048
	ds_read_b128 v[156:159], v156 offset:3072
	ds_read_b128 v[162:165], v174
	ds_read_b128 v[166:169], v174 offset:1024
	ds_read_b128 v[170:173], v174 offset:2048
	ds_read_b128 v[174:177], v174 offset:3072
	s_add_u32 s24, s58, 0x40000
	s_addc_u32 s25, s59, 0
	s_mov_b32 m0, s64
	v_lshl_add_u64 v[216:217], s[24:25], 0, v[128:129]
	ds_read_b128 v[178:181], v147 offset:32768
	ds_read_b128 v[182:185], v147 offset:33792
	ds_read_b128 v[186:189], v147 offset:34816
	ds_read_b128 v[190:193], v147 offset:35840
	ds_read_b128 v[194:197], v147 offset:36864
	ds_read_b128 v[198:201], v147 offset:37888
	ds_read_b128 v[202:205], v147 offset:38912
	ds_read_b128 v[206:209], v147 offset:39936
	global_load_lds_dwordx4 v[216:217], off
	v_lshl_add_u64 v[216:217], s[24:25], 0, v[130:131]
	s_mov_b32 m0, s65
	s_nop 0
	global_load_lds_dwordx4 v[216:217], off
	s_waitcnt vmcnt(8)
	s_waitcnt lgkmcnt(0)
	s_barrier
	s_setprio 1
	s_waitcnt lgkmcnt(0)
	v_mfma_f32_16x16x32_bf16 v[124:127], v[138:141], v[178:181], v[124:127]
	v_mfma_f32_16x16x32_bf16 v[120:123], v[152:155], v[178:181], v[120:123]
	v_mfma_f32_16x16x32_bf16 v[108:111], v[138:141], v[186:189], v[108:111]
	v_mfma_f32_16x16x32_bf16 v[104:107], v[152:155], v[186:189], v[104:107]
	v_mfma_f32_16x16x32_bf16 v[92:95], v[138:141], v[194:197], v[92:95]
	v_mfma_f32_16x16x32_bf16 v[88:91], v[152:155], v[194:197], v[88:91]
	v_mfma_f32_16x16x32_bf16 v[76:79], v[138:141], v[202:205], v[76:79]
	v_mfma_f32_16x16x32_bf16 v[72:75], v[152:155], v[202:205], v[72:75]
	v_mfma_f32_16x16x32_bf16 v[124:127], v[148:151], v[182:185], v[124:127]
	v_mfma_f32_16x16x32_bf16 v[120:123], v[156:159], v[182:185], v[120:123]
	v_mfma_f32_16x16x32_bf16 v[108:111], v[148:151], v[190:193], v[108:111]
	v_mfma_f32_16x16x32_bf16 v[104:107], v[156:159], v[190:193], v[104:107]
	v_mfma_f32_16x16x32_bf16 v[92:95], v[148:151], v[198:201], v[92:95]
	v_mfma_f32_16x16x32_bf16 v[88:91], v[156:159], v[198:201], v[88:91]
	v_mfma_f32_16x16x32_bf16 v[76:79], v[148:151], v[206:209], v[76:79]
	v_mfma_f32_16x16x32_bf16 v[72:75], v[156:159], v[206:209], v[72:75]
	v_mfma_f32_16x16x32_bf16 v[116:119], v[162:165], v[178:181], v[116:119]
	v_mfma_f32_16x16x32_bf16 v[112:115], v[170:173], v[178:181], v[112:115]
	v_mfma_f32_16x16x32_bf16 v[100:103], v[162:165], v[186:189], v[100:103]
	v_mfma_f32_16x16x32_bf16 v[96:99], v[170:173], v[186:189], v[96:99]
	v_mfma_f32_16x16x32_bf16 v[84:87], v[162:165], v[194:197], v[84:87]
	v_mfma_f32_16x16x32_bf16 v[80:83], v[170:173], v[194:197], v[80:83]
	v_mfma_f32_16x16x32_bf16 v[68:71], v[162:165], v[202:205], v[68:71]
	v_mfma_f32_16x16x32_bf16 v[64:67], v[170:173], v[202:205], v[64:67]
	v_mfma_f32_16x16x32_bf16 v[116:119], v[166:169], v[182:185], v[116:119]
	v_mfma_f32_16x16x32_bf16 v[112:115], v[174:177], v[182:185], v[112:115]
	v_mfma_f32_16x16x32_bf16 v[100:103], v[166:169], v[190:193], v[100:103]
	v_mfma_f32_16x16x32_bf16 v[96:99], v[174:177], v[190:193], v[96:99]
	v_mfma_f32_16x16x32_bf16 v[84:87], v[166:169], v[198:201], v[84:87]
	v_mfma_f32_16x16x32_bf16 v[80:83], v[174:177], v[198:201], v[80:83]
	v_mfma_f32_16x16x32_bf16 v[68:71], v[166:169], v[206:209], v[68:71]
	v_mfma_f32_16x16x32_bf16 v[64:67], v[174:177], v[206:209], v[64:67]
	s_setprio 0
	s_barrier
; #define PG8_STAGE(bufoff, gbase, voff) do { _Pragma("unroll") for (int _i = 0; _i < 2; ++_i) \
;         __builtin_amdgcn_global_load_lds((const unsigned*)((const char*)(gbase) + (voff)[_i]), (PG8_LAS unsigned*)(lds + (bufoff) + ldsw + _i * 8192), 16, 0, 0); } while (0)
; #define PG8_LDA(dst, b, h) do { _Pragma("unroll") for (int m = 0; m < 4; ++m) _Pragma("unroll") for (int k = 0; k < 2; ++k) dst[m][k] = *(const PG8_LAS bf16x8*)(lds + PG8_SA(b, h) + aoff + m * 2048 + k * 1024); } while (0)
; #define PG8_MMA(ai, bj, At, Bt) do { __builtin_amdgcn_s_setprio(1); _Pragma("unroll") for (int m = 0; m < 4; ++m) _Pragma("unroll") for (int n = 0; n < 2; ++n) _Pragma("unroll") for (int k = 0; k < 2; ++k) \
;         acc[ai][bj][m][n] = __builtin_amdgcn_mfma_f32_16x16x32_bf16(Bt[n][k], At[m][k], acc[ai][bj][m][n], 0, 0, 0); __builtin_amdgcn_s_setprio(0); } while (0)
; #define PG8_WAIT_V(n) asm volatile("s_waitcnt vmcnt(" #n ")" ::: "memory")
; #define PG8_WAIT_L(n) asm volatile("s_waitcnt lgkmcnt(" #n ")" ::: "memory")
; #define PG8_BAR __builtin_amdgcn_s_barrier()
; #define PG8_SCHED __builtin_amdgcn_sched_barrier(0)
; template <class Epi, class Sched, bool ALIGN_EPI = false, bool SP2 = false>
; __device__ __forceinline__ void gemm_phase(PG8_LAS unsigned char* lds, const Gemm g, const Sched& S, const Epi& E, const int wid_in) {
;     ...
;             PG8_WAIT_V(8); PG8_WAIT_L(0); PG8_BAR; PG8_MMA(0, 0, At, B0); PG8_MMA(0, 1, At, B1); PG8_BAR; PG8_SCHED;
;             PG8_LDA(At, 1, 1); PG8_STAGE(PG8_SB(1, 0), b3, voffB); PG8_STAGE(PG8_SB(1, 1), b3 + hstep, voffB); PG8_STAGE(PG8_SA(1, 0), a3, voffA);
;             PG8_WAIT_V(8); PG8_WAIT_L(0); PG8_BAR; PG8_MMA(1, 0, At, B0); PG8_MMA(1, 1, At, B1); PG8_BAR; PG8_SCHED;
	s_add_i32 s24, s26, s62
	v_lshl_add_u64 v[142:143], v[142:143], 0, s[8:9]
	s_mov_b32 m0, s24
	ds_read_b128 v[178:181], v147 offset:49152
	ds_read_b128 v[182:185], v147 offset:50176
	ds_read_b128 v[186:189], v147 offset:51200
	ds_read_b128 v[190:193], v147 offset:52224
	ds_read_b128 v[194:197], v147 offset:53248
	ds_read_b128 v[198:201], v147 offset:54272
	ds_read_b128 v[202:205], v147 offset:55296
	ds_read_b128 v[206:209], v147 offset:56320
	global_load_lds_dwordx4 v[142:143], off
	s_add_i32 m0, s24, 0x2000
	s_add_u32 s24, s56, 0x40080
	v_lshl_add_u64 v[142:143], v[210:211], 0, s[8:9]
	s_addc_u32 s25, s57, 0
	s_add_i32 s26, s27, s62
	global_load_lds_dwordx4 v[142:143], off
	v_lshl_add_u64 v[142:143], s[24:25], 0, v[160:161]
	s_mov_b32 m0, s26
	s_nop 0
	global_load_lds_dwordx4 v[142:143], off
	v_lshl_add_u64 v[142:143], s[24:25], 0, v[132:133]
	s_add_i32 m0, s26, 0x2000
	s_nop 0
	global_load_lds_dwordx4 v[142:143], off
	v_lshl_add_u64 v[142:143], v[212:213], 0, s[8:9]
	s_mov_b32 m0, s66
	s_nop 0
	global_load_lds_dwordx4 v[142:143], off
	v_lshl_add_u64 v[142:143], v[214:215], 0, s[8:9]
	s_mov_b32 m0, s67
	s_nop 0
	global_load_lds_dwordx4 v[142:143], off
	s_waitcnt vmcnt(8)
	s_waitcnt lgkmcnt(0)
	s_barrier
	s_setprio 1
	s_waitcnt lgkmcnt(0)
	v_mfma_f32_16x16x32_bf16 v[60:63], v[138:141], v[178:181], v[60:63]
	v_mfma_f32_16x16x32_bf16 v[56:59], v[152:155], v[178:181], v[56:59]
	v_mfma_f32_16x16x32_bf16 v[44:47], v[138:141], v[186:189], v[44:47]
	v_mfma_f32_16x16x32_bf16 v[40:43], v[152:155], v[186:189], v[40:43]
	v_mfma_f32_16x16x32_bf16 v[28:31], v[138:141], v[194:197], v[28:31]
	v_mfma_f32_16x16x32_bf16 v[24:27], v[152:155], v[194:197], v[24:27]
	v_mfma_f32_16x16x32_bf16 v[12:15], v[138:141], v[202:205], v[12:15]
	v_mfma_f32_16x16x32_bf16 v[8:11], v[152:155], v[202:205], v[8:11]
	v_mfma_f32_16x16x32_bf16 v[60:63], v[148:151], v[182:185], v[60:63]
	v_mfma_f32_16x16x32_bf16 v[56:59], v[156:159], v[182:185], v[56:59]
	v_mfma_f32_16x16x32_bf16 v[44:47], v[148:151], v[190:193], v[44:47]
	v_mfma_f32_16x16x32_bf16 v[40:43], v[156:159], v[190:193], v[40:43]
	v_mfma_f32_16x16x32_bf16 v[28:31], v[148:151], v[198:201], v[28:31]
	v_mfma_f32_16x16x32_bf16 v[24:27], v[156:159], v[198:201], v[24:27]
	v_mfma_f32_16x16x32_bf16 v[12:15], v[148:151], v[206:209], v[12:15]
	v_mfma_f32_16x16x32_bf16 v[8:11], v[156:159], v[206:209], v[8:11]
	v_mfma_f32_16x16x32_bf16 v[52:55], v[162:165], v[178:181], v[52:55]
	v_mfma_f32_16x16x32_bf16 v[48:51], v[170:173], v[178:181], v[48:51]
	v_mfma_f32_16x16x32_bf16 v[36:39], v[162:165], v[186:189], v[36:39]
	v_mfma_f32_16x16x32_bf16 v[32:35], v[170:173], v[186:189], v[32:35]
	v_mfma_f32_16x16x32_bf16 v[20:23], v[162:165], v[194:197], v[20:23]
	v_mfma_f32_16x16x32_bf16 v[16:19], v[170:173], v[194:197], v[16:19]
	v_mfma_f32_16x16x32_bf16 v[4:7], v[162:165], v[202:205], v[4:7]
	v_mfma_f32_16x16x32_bf16 v[0:3], v[170:173], v[202:205], v[0:3]
	v_mfma_f32_16x16x32_bf16 v[52:55], v[166:169], v[182:185], v[52:55]
	v_mfma_f32_16x16x32_bf16 v[48:51], v[174:177], v[182:185], v[48:51]
	v_mfma_f32_16x16x32_bf16 v[36:39], v[166:169], v[190:193], v[36:39]
	v_mfma_f32_16x16x32_bf16 v[32:35], v[174:177], v[190:193], v[32:35]
	v_mfma_f32_16x16x32_bf16 v[20:23], v[166:169], v[198:201], v[20:23]
	v_mfma_f32_16x16x32_bf16 v[16:19], v[174:177], v[198:201], v[16:19]
	v_mfma_f32_16x16x32_bf16 v[4:7], v[166:169], v[206:209], v[4:7]
	v_mfma_f32_16x16x32_bf16 v[0:3], v[174:177], v[206:209], v[0:3]
	s_setprio 0
	s_barrier
	s_add_i32 s71, s71, 2
	s_add_u32 s54, s54, 0x100
	s_addc_u32 s55, s55, 0
	s_add_u32 s69, s69, 0x100
	s_addc_u32 s70, s70, 0
	s_cmp_gt_u32 s71, 13
	s_cbranch_scc0 .LBB0_527
	s_and_b64 vcc, exec, s[42:43]
	s_cbranch_vccz .LBB0_530
	s_barrier

; #define PG8_STAGE(bufoff, gbase, voff) do { _Pragma("unroll") for (int _i = 0; _i < 2; ++_i) \
;         __builtin_amdgcn_global_load_lds((const unsigned*)((const char*)(gbase) + (voff)[_i]), (PG8_LAS unsigned*)(lds + (bufoff) + ldsw + _i * 8192), 16, 0, 0); } while (0)
; #define PG8_LDA(dst, b, h) do { _Pragma("unroll") for (int m = 0; m < 4; ++m) _Pragma("unroll") for (int k = 0; k < 2; ++k) dst[m][k] = *(const PG8_LAS bf16x8*)(lds + PG8_SA(b, h) + aoff + m * 2048 + k * 1024); } while (0)
; #define PG8_LDB(dst, b, h) do { _Pragma("unroll") for (int n = 0; n < 2; ++n) _Pragma("unroll") for (int k = 0; k < 2; ++k) dst[n][k] = *(const PG8_LAS bf16x8*)(lds + PG8_SB(b, h) + boff + n * 2048 + k * 1024); } while (0)
; #define PG8_MMA(ai, bj, At, Bt) do { __builtin_amdgcn_s_setprio(1); _Pragma("unroll") for (int m = 0; m < 4; ++m) _Pragma("unroll") for (int n = 0; n < 2; ++n) _Pragma("unroll") for (int k = 0; k < 2; ++k) \
;         acc[ai][bj][m][n] = __builtin_amdgcn_mfma_f32_16x16x32_bf16(Bt[n][k], At[m][k], acc[ai][bj][m][n], 0, 0, 0); __builtin_amdgcn_s_setprio(0); } while (0)
; #define PG8_WAIT_V(n) asm volatile("s_waitcnt vmcnt(" #n ")" ::: "memory")
; #define PG8_WAIT_L(n) asm volatile("s_waitcnt lgkmcnt(" #n ")" ::: "memory")
; #define PG8_BAR __builtin_amdgcn_s_barrier()
; template <class Epi, class Sched, bool ALIGN_EPI = false, bool SP2 = false>
; __device__ __forceinline__ void gemm_phase(PG8_LAS unsigned char* lds, const Gemm g, const Sched& S, const Epi& E, const int wid_in) {
;     ...
;         for (int t = 0; t < nt; t += 2) {
;             const bool last = (t == nt - 2);
;             const char* a1 = cA + (size_t)(t + 1) * kstep;
;             const char* a2 = last ? nA : cA + (size_t)(t + 2) * kstep; const char* b2 = last ? nB : cB + (size_t)(t + 2) * kstep;
;             const char* a3 = a2 + kstep; const char* b3 = b2 + kstep;
;             if (last && has_next) S.a_ready(nxt);
;             if constexpr (SP2) {
;             PG8_LDB(B0, 0, 0); PG8_LDB(B1, 0, 1); PG8_SCHED; PG8_LDA(At, 0, 0); PG8_STAGE(PG8_SA(1, 1), a1 + hstep, voffA);
;             PG8_WAIT_V(8); PG8_WAIT_L(0); PG8_BAR; PG8_MMA(0, 0, At, B0); PG8_MMA(0, 1, At, B1); PG8_BAR; PG8_SCHED;
;             PG8_LDA(At, 0, 1); PG8_STAGE(PG8_SB(0, 0), b2, voffB); PG8_STAGE(PG8_SB(0, 1), b2 + hstep, voffB); PG8_STAGE(PG8_SA(0, 0), a2, voffA);
.LBB0_674:
	s_add_u32 s24, s58, 0xfff80080
	s_addc_u32 s25, s59, -1
	s_add_i32 s26, 0, 0x10000
	s_cmp_eq_u32 s73, 28
	s_cselect_b32 s63, s14, s25
	s_cselect_b32 s62, s15, s24
	s_cselect_b32 s61, s49, s72
	s_cselect_b32 s60, s51, s71
	s_add_i32 s27, 0, 0x14000
	v_add_u32_e32 v154, s26, v143
	v_add_u32_e32 v158, s27, v143
	ds_read_b128 v[138:141], v154
	ds_read_b128 v[146:149], v154 offset:1024
	ds_read_b128 v[150:153], v154 offset:2048
	ds_read_b128 v[154:157], v154 offset:3072
	ds_read_b128 v[162:165], v158
	ds_read_b128 v[166:169], v158 offset:1024
	ds_read_b128 v[170:173], v158 offset:2048
	ds_read_b128 v[174:177], v158 offset:3072
	v_lshl_add_u64 v[158:159], s[58:59], 0, v[134:135]
	s_add_i32 m0, s57, 0xc000
	ds_read_b128 v[178:181], v145
	ds_read_b128 v[182:185], v145 offset:1024
	ds_read_b128 v[186:189], v145 offset:2048
	ds_read_b128 v[190:193], v145 offset:3072
	ds_read_b128 v[194:197], v145 offset:4096
	ds_read_b128 v[198:201], v145 offset:5120
	ds_read_b128 v[202:205], v145 offset:6144
	ds_read_b128 v[206:209], v145 offset:7168
	global_load_lds_dwordx4 v[158:159], off
	v_lshl_add_u64 v[158:159], s[58:59], 0, v[136:137]
	s_add_i32 m0, s57, 0xe000
	s_nop 0
	global_load_lds_dwordx4 v[158:159], off
	s_waitcnt vmcnt(8)
	s_waitcnt lgkmcnt(0)
	s_barrier
	s_setprio 1
	s_waitcnt lgkmcnt(0)
	v_mfma_f32_16x16x32_bf16 v[124:127], v[138:141], v[178:181], v[124:127]
	v_mfma_f32_16x16x32_bf16 v[120:123], v[150:153], v[178:181], v[120:123]
	v_mfma_f32_16x16x32_bf16 v[116:119], v[138:141], v[186:189], v[116:119]
	v_mfma_f32_16x16x32_bf16 v[108:111], v[150:153], v[186:189], v[108:111]
	v_mfma_f32_16x16x32_bf16 v[100:103], v[138:141], v[194:197], v[100:103]
	v_mfma_f32_16x16x32_bf16 v[92:95], v[150:153], v[194:197], v[92:95]
	v_mfma_f32_16x16x32_bf16 v[84:87], v[138:141], v[202:205], v[84:87]
	v_mfma_f32_16x16x32_bf16 v[76:79], v[150:153], v[202:205], v[76:79]
	v_mfma_f32_16x16x32_bf16 v[124:127], v[146:149], v[182:185], v[124:127]
	v_mfma_f32_16x16x32_bf16 v[120:123], v[154:157], v[182:185], v[120:123]
	v_mfma_f32_16x16x32_bf16 v[116:119], v[146:149], v[190:193], v[116:119]
	v_mfma_f32_16x16x32_bf16 v[108:111], v[154:157], v[190:193], v[108:111]
	v_mfma_f32_16x16x32_bf16 v[100:103], v[146:149], v[198:201], v[100:103]
	v_mfma_f32_16x16x32_bf16 v[92:95], v[154:157], v[198:201], v[92:95]
	v_mfma_f32_16x16x32_bf16 v[84:87], v[146:149], v[206:209], v[84:87]
	v_mfma_f32_16x16x32_bf16 v[76:79], v[154:157], v[206:209], v[76:79]
	v_mfma_f32_16x16x32_bf16 v[112:115], v[162:165], v[178:181], v[112:115]
	v_mfma_f32_16x16x32_bf16 v[104:107], v[170:173], v[178:181], v[104:107]
	v_mfma_f32_16x16x32_bf16 v[96:99], v[162:165], v[186:189], v[96:99]
	v_mfma_f32_16x16x32_bf16 v[88:91], v[170:173], v[186:189], v[88:91]
	v_mfma_f32_16x16x32_bf16 v[80:83], v[162:165], v[194:197], v[80:83]
	v_mfma_f32_16x16x32_bf16 v[72:75], v[170:173], v[194:197], v[72:75]
	v_mfma_f32_16x16x32_bf16 v[68:71], v[162:165], v[202:205], v[68:71]
	v_mfma_f32_16x16x32_bf16 v[64:67], v[170:173], v[202:205], v[64:67]
	v_mfma_f32_16x16x32_bf16 v[112:115], v[166:169], v[182:185], v[112:115]
	v_mfma_f32_16x16x32_bf16 v[104:107], v[174:177], v[182:185], v[104:107]
	v_mfma_f32_16x16x32_bf16 v[96:99], v[166:169], v[190:193], v[96:99]
	v_mfma_f32_16x16x32_bf16 v[88:91], v[174:177], v[190:193], v[88:91]
	v_mfma_f32_16x16x32_bf16 v[80:83], v[166:169], v[198:201], v[80:83]
	v_mfma_f32_16x16x32_bf16 v[72:75], v[174:177], v[198:201], v[72:75]
	v_mfma_f32_16x16x32_bf16 v[68:71], v[166:169], v[206:209], v[68:71]
	v_mfma_f32_16x16x32_bf16 v[64:67], v[174:177], v[206:209], v[64:67]
	s_setprio 0
	s_barrier
	s_add_i32 s24, s26, s35
	v_lshl_add_u64 v[158:159], s[60:61], 0, v[160:161]
	s_mov_b32 m0, s24
	ds_read_b128 v[178:181], v145 offset:16384
	ds_read_b128 v[182:185], v145 offset:17408
	ds_read_b128 v[186:189], v145 offset:18432
	ds_read_b128 v[190:193], v145 offset:19456
	ds_read_b128 v[194:197], v145 offset:20480
	ds_read_b128 v[198:201], v145 offset:21504
	ds_read_b128 v[202:205], v145 offset:22528
	ds_read_b128 v[206:209], v145 offset:23552
	global_load_lds_dwordx4 v[158:159], off
	s_add_i32 m0, s24, 0x2000
	s_add_u32 s24, s60, 0x80000
	v_lshl_add_u64 v[210:211], s[60:61], 0, v[132:133]
	s_addc_u32 s25, s61, 0
	s_add_i32 s26, s27, s35
	global_load_lds_dwordx4 v[210:211], off
	v_lshl_add_u64 v[212:213], s[24:25], 0, v[160:161]
	s_mov_b32 m0, s26
	v_lshl_add_u64 v[214:215], s[62:63], 0, v[130:131]
	global_load_lds_dwordx4 v[212:213], off
	v_lshl_add_u64 v[212:213], s[24:25], 0, v[132:133]
	s_add_i32 m0, s26, 0x2000
	s_nop 0
	global_load_lds_dwordx4 v[212:213], off
	v_lshl_add_u64 v[212:213], s[62:63], 0, v[128:129]
	s_mov_b32 m0, s57
	s_nop 0
	global_load_lds_dwordx4 v[212:213], off
	s_mov_b32 m0, s64
	s_nop 0
	global_load_lds_dwordx4 v[214:215], off
	s_waitcnt vmcnt(8)
	s_waitcnt lgkmcnt(0)
	s_barrier
; #define PG8_STAGE(bufoff, gbase, voff) do { _Pragma("unroll") for (int _i = 0; _i < 2; ++_i) \
;         __builtin_amdgcn_global_load_lds((const unsigned*)((const char*)(gbase) + (voff)[_i]), (PG8_LAS unsigned*)(lds + (bufoff) + ldsw + _i * 8192), 16, 0, 0); } while (0)
; #define PG8_LDA(dst, b, h) do { _Pragma("unroll") for (int m = 0; m < 4; ++m) _Pragma("unroll") for (int k = 0; k < 2; ++k) dst[m][k] = *(const PG8_LAS bf16x8*)(lds + PG8_SA(b, h) + aoff + m * 2048 + k * 1024); } while (0)
; #define PG8_LDB(dst, b, h) do { _Pragma("unroll") for (int n = 0; n < 2; ++n) _Pragma("unroll") for (int k = 0; k < 2; ++k) dst[n][k] = *(const PG8_LAS bf16x8*)(lds + PG8_SB(b, h) + boff + n * 2048 + k * 1024); } while (0)
; #define PG8_MMA(ai, bj, At, Bt) do { __builtin_amdgcn_s_setprio(1); _Pragma("unroll") for (int m = 0; m < 4; ++m) _Pragma("unroll") for (int n = 0; n < 2; ++n) _Pragma("unroll") for (int k = 0; k < 2; ++k) \
;         acc[ai][bj][m][n] = __builtin_amdgcn_mfma_f32_16x16x32_bf16(Bt[n][k], At[m][k], acc[ai][bj][m][n], 0, 0, 0); __builtin_amdgcn_s_setprio(0); } while (0)
; #define PG8_WAIT_V(n) asm volatile("s_waitcnt vmcnt(" #n ")" ::: "memory")
; #define PG8_WAIT_L(n) asm volatile("s_waitcnt lgkmcnt(" #n ")" ::: "memory")
; #define PG8_BAR __builtin_amdgcn_s_barrier()
; #define PG8_SCHED __builtin_amdgcn_sched_barrier(0)
; template <class Epi, class Sched, bool ALIGN_EPI = false, bool SP2 = false>
; __device__ __forceinline__ void gemm_phase(PG8_LAS unsigned char* lds, const Gemm g, const Sched& S, const Epi& E, const int wid_in) {
;     ...
;             PG8_WAIT_V(8); PG8_WAIT_L(0); PG8_BAR; PG8_MMA(1, 0, At, B0); PG8_MMA(1, 1, At, B1); PG8_BAR; PG8_SCHED;
;             PG8_LDB(B0, 1, 0); PG8_LDB(B1, 1, 1); PG8_SCHED; PG8_LDA(At, 1, 0); PG8_STAGE(PG8_SA(0, 1), a2 + hstep, voffA);
;             PG8_WAIT_V(8); PG8_WAIT_L(0); PG8_BAR; PG8_MMA(0, 0, At, B0); PG8_MMA(0, 1, At, B1); PG8_BAR; PG8_SCHED;
	s_setprio 1
	s_waitcnt lgkmcnt(0)
	v_mfma_f32_16x16x32_bf16 v[60:63], v[138:141], v[178:181], v[60:63]
	v_mfma_f32_16x16x32_bf16 v[56:59], v[150:153], v[178:181], v[56:59]
	v_mfma_f32_16x16x32_bf16 v[52:55], v[138:141], v[186:189], v[52:55]
	v_mfma_f32_16x16x32_bf16 v[44:47], v[150:153], v[186:189], v[44:47]
	v_mfma_f32_16x16x32_bf16 v[36:39], v[138:141], v[194:197], v[36:39]
	v_mfma_f32_16x16x32_bf16 v[28:31], v[150:153], v[194:197], v[28:31]
	v_mfma_f32_16x16x32_bf16 v[20:23], v[138:141], v[202:205], v[20:23]
	v_mfma_f32_16x16x32_bf16 v[12:15], v[150:153], v[202:205], v[12:15]
	v_mfma_f32_16x16x32_bf16 v[60:63], v[146:149], v[182:185], v[60:63]
	v_mfma_f32_16x16x32_bf16 v[56:59], v[154:157], v[182:185], v[56:59]
	v_mfma_f32_16x16x32_bf16 v[52:55], v[146:149], v[190:193], v[52:55]
	v_mfma_f32_16x16x32_bf16 v[44:47], v[154:157], v[190:193], v[44:47]
	v_mfma_f32_16x16x32_bf16 v[36:39], v[146:149], v[198:201], v[36:39]
	v_mfma_f32_16x16x32_bf16 v[28:31], v[154:157], v[198:201], v[28:31]
	v_mfma_f32_16x16x32_bf16 v[20:23], v[146:149], v[206:209], v[20:23]
	v_mfma_f32_16x16x32_bf16 v[12:15], v[154:157], v[206:209], v[12:15]
	v_mfma_f32_16x16x32_bf16 v[48:51], v[162:165], v[178:181], v[48:51]
	v_mfma_f32_16x16x32_bf16 v[40:43], v[170:173], v[178:181], v[40:43]
	v_mfma_f32_16x16x32_bf16 v[32:35], v[162:165], v[186:189], v[32:35]
	v_mfma_f32_16x16x32_bf16 v[24:27], v[170:173], v[186:189], v[24:27]
	v_mfma_f32_16x16x32_bf16 v[16:19], v[162:165], v[194:197], v[16:19]
	v_mfma_f32_16x16x32_bf16 v[8:11], v[170:173], v[194:197], v[8:11]
	v_mfma_f32_16x16x32_bf16 v[4:7], v[162:165], v[202:205], v[4:7]
	v_mfma_f32_16x16x32_bf16 v[0:3], v[170:173], v[202:205], v[0:3]
	v_mfma_f32_16x16x32_bf16 v[48:51], v[166:169], v[182:185], v[48:51]
	v_mfma_f32_16x16x32_bf16 v[40:43], v[174:177], v[182:185], v[40:43]
	v_mfma_f32_16x16x32_bf16 v[32:35], v[166:169], v[190:193], v[32:35]
	v_mfma_f32_16x16x32_bf16 v[24:27], v[174:177], v[190:193], v[24:27]
	v_mfma_f32_16x16x32_bf16 v[16:19], v[166:169], v[198:201], v[16:19]
	v_mfma_f32_16x16x32_bf16 v[8:11], v[174:177], v[198:201], v[8:11]
	v_mfma_f32_16x16x32_bf16 v[4:7], v[166:169], v[206:209], v[4:7]
	v_mfma_f32_16x16x32_bf16 v[0:3], v[174:177], v[206:209], v[0:3]
	s_setprio 0
	s_barrier
	s_add_i32 s26, 0, 0x18000
	s_add_i32 s27, 0, 0x1c000
	v_add_u32_e32 v154, s26, v143
	v_add_u32_e32 v174, s27, v143
	ds_read_b128 v[138:141], v154
	ds_read_b128 v[146:149], v154 offset:1024
	ds_read_b128 v[150:153], v154 offset:2048
	ds_read_b128 v[154:157], v154 offset:3072
	ds_read_b128 v[162:165], v174
	ds_read_b128 v[166:169], v174 offset:1024
	ds_read_b128 v[170:173], v174 offset:2048
	ds_read_b128 v[174:177], v174 offset:3072
	s_add_u32 s24, s62, 0x80000
	s_addc_u32 s25, s63, 0
	s_mov_b32 m0, s65
	v_lshl_add_u64 v[216:217], s[24:25], 0, v[128:129]
	ds_read_b128 v[178:181], v145 offset:32768
	ds_read_b128 v[182:185], v145 offset:33792
	ds_read_b128 v[186:189], v145 offset:34816
	ds_read_b128 v[190:193], v145 offset:35840
	ds_read_b128 v[194:197], v145 offset:36864
	ds_read_b128 v[198:201], v145 offset:37888
	ds_read_b128 v[202:205], v145 offset:38912
	ds_read_b128 v[206:209], v145 offset:39936
	global_load_lds_dwordx4 v[216:217], off
	v_lshl_add_u64 v[216:217], s[24:25], 0, v[130:131]
	s_mov_b32 m0, s66
	s_nop 0
	global_load_lds_dwordx4 v[216:217], off
	s_waitcnt vmcnt(8)
	s_waitcnt lgkmcnt(0)
	s_barrier
	s_setprio 1
	s_waitcnt lgkmcnt(0)
	v_mfma_f32_16x16x32_bf16 v[124:127], v[138:141], v[178:181], v[124:127]
	v_mfma_f32_16x16x32_bf16 v[120:123], v[150:153], v[178:181], v[120:123]
	v_mfma_f32_16x16x32_bf16 v[116:119], v[138:141], v[186:189], v[116:119]
	v_mfma_f32_16x16x32_bf16 v[108:111], v[150:153], v[186:189], v[108:111]
	v_mfma_f32_16x16x32_bf16 v[100:103], v[138:141], v[194:197], v[100:103]
	v_mfma_f32_16x16x32_bf16 v[92:95], v[150:153], v[194:197], v[92:95]
	v_mfma_f32_16x16x32_bf16 v[84:87], v[138:141], v[202:205], v[84:87]
	v_mfma_f32_16x16x32_bf16 v[76:79], v[150:153], v[202:205], v[76:79]
	v_mfma_f32_16x16x32_bf16 v[124:127], v[146:149], v[182:185], v[124:127]
	v_mfma_f32_16x16x32_bf16 v[120:123], v[154:157], v[182:185], v[120:123]
	v_mfma_f32_16x16x32_bf16 v[116:119], v[146:149], v[190:193], v[116:119]
	v_mfma_f32_16x16x32_bf16 v[108:111], v[154:157], v[190:193], v[108:111]
	v_mfma_f32_16x16x32_bf16 v[100:103], v[146:149], v[198:201], v[100:103]
	v_mfma_f32_16x16x32_bf16 v[92:95], v[154:157], v[198:201], v[92:95]
	v_mfma_f32_16x16x32_bf16 v[84:87], v[146:149], v[206:209], v[84:87]
	v_mfma_f32_16x16x32_bf16 v[76:79], v[154:157], v[206:209], v[76:79]
	v_mfma_f32_16x16x32_bf16 v[112:115], v[162:165], v[178:181], v[112:115]
	v_mfma_f32_16x16x32_bf16 v[104:107], v[170:173], v[178:181], v[104:107]
	v_mfma_f32_16x16x32_bf16 v[96:99], v[162:165], v[186:189], v[96:99]
	v_mfma_f32_16x16x32_bf16 v[88:91], v[170:173], v[186:189], v[88:91]
	v_mfma_f32_16x16x32_bf16 v[80:83], v[162:165], v[194:197], v[80:83]
	v_mfma_f32_16x16x32_bf16 v[72:75], v[170:173], v[194:197], v[72:75]
	v_mfma_f32_16x16x32_bf16 v[68:71], v[162:165], v[202:205], v[68:71]
	v_mfma_f32_16x16x32_bf16 v[64:67], v[170:173], v[202:205], v[64:67]
	v_mfma_f32_16x16x32_bf16 v[112:115], v[166:169], v[182:185], v[112:115]
	v_mfma_f32_16x16x32_bf16 v[104:107], v[174:177], v[182:185], v[104:107]
	v_mfma_f32_16x16x32_bf16 v[96:99], v[166:169], v[190:193], v[96:99]
	v_mfma_f32_16x16x32_bf16 v[88:91], v[174:177], v[190:193], v[88:91]
	v_mfma_f32_16x16x32_bf16 v[80:83], v[166:169], v[198:201], v[80:83]
	v_mfma_f32_16x16x32_bf16 v[72:75], v[174:177], v[198:201], v[72:75]
	v_mfma_f32_16x16x32_bf16 v[68:71], v[166:169], v[206:209], v[68:71]
	v_mfma_f32_16x16x32_bf16 v[64:67], v[174:177], v[206:209], v[64:67]
	s_setprio 0
	s_barrier
; #define PG8_STAGE(bufoff, gbase, voff) do { _Pragma("unroll") for (int _i = 0; _i < 2; ++_i) \
;         __builtin_amdgcn_global_load_lds((const unsigned*)((const char*)(gbase) + (voff)[_i]), (PG8_LAS unsigned*)(lds + (bufoff) + ldsw + _i * 8192), 16, 0, 0); } while (0)
; #define PG8_LDA(dst, b, h) do { _Pragma("unroll") for (int m = 0; m < 4; ++m) _Pragma("unroll") for (int k = 0; k < 2; ++k) dst[m][k] = *(const PG8_LAS bf16x8*)(lds + PG8_SA(b, h) + aoff + m * 2048 + k * 1024); } while (0)
; #define PG8_MMA(ai, bj, At, Bt) do { __builtin_amdgcn_s_setprio(1); _Pragma("unroll") for (int m = 0; m < 4; ++m) _Pragma("unroll") for (int n = 0; n < 2; ++n) _Pragma("unroll") for (int k = 0; k < 2; ++k) \
;         acc[ai][bj][m][n] = __builtin_amdgcn_mfma_f32_16x16x32_bf16(Bt[n][k], At[m][k], acc[ai][bj][m][n], 0, 0, 0); __builtin_amdgcn_s_setprio(0); } while (0)
; #define PG8_WAIT_V(n) asm volatile("s_waitcnt vmcnt(" #n ")" ::: "memory")
; #define PG8_WAIT_L(n) asm volatile("s_waitcnt lgkmcnt(" #n ")" ::: "memory")
; #define PG8_BAR __builtin_amdgcn_s_barrier()
; #define PG8_SCHED __builtin_amdgcn_sched_barrier(0)
; template <class Epi, class Sched, bool ALIGN_EPI = false, bool SP2 = false>
; __device__ __forceinline__ void gemm_phase(PG8_LAS unsigned char* lds, const Gemm g, const Sched& S, const Epi& E, const int wid_in) {
;     ...
;             PG8_WAIT_V(8); PG8_WAIT_L(0); PG8_BAR; PG8_MMA(0, 0, At, B0); PG8_MMA(0, 1, At, B1); PG8_BAR; PG8_SCHED;
;             PG8_LDA(At, 1, 1); PG8_STAGE(PG8_SB(1, 0), b3, voffB); PG8_STAGE(PG8_SB(1, 1), b3 + hstep, voffB); PG8_STAGE(PG8_SA(1, 0), a3, voffA);
;             PG8_WAIT_V(8); PG8_WAIT_L(0); PG8_BAR; PG8_MMA(1, 0, At, B0); PG8_MMA(1, 1, At, B1); PG8_BAR; PG8_SCHED;
	s_add_i32 s24, s26, s35
	v_lshl_add_u64 v[158:159], v[158:159], 0, s[8:9]
	s_mov_b32 m0, s24
	ds_read_b128 v[178:181], v145 offset:49152
	ds_read_b128 v[182:185], v145 offset:50176
	ds_read_b128 v[186:189], v145 offset:51200
	ds_read_b128 v[190:193], v145 offset:52224
	ds_read_b128 v[194:197], v145 offset:53248
	ds_read_b128 v[198:201], v145 offset:54272
	ds_read_b128 v[202:205], v145 offset:55296
	ds_read_b128 v[206:209], v145 offset:56320
	global_load_lds_dwordx4 v[158:159], off
	s_add_i32 m0, s24, 0x2000
	s_add_u32 s24, s60, 0x80080
	v_lshl_add_u64 v[158:159], v[210:211], 0, s[8:9]
	s_addc_u32 s25, s61, 0
	s_add_i32 s26, s27, s35
	global_load_lds_dwordx4 v[158:159], off
	v_lshl_add_u64 v[158:159], s[24:25], 0, v[160:161]
	s_mov_b32 m0, s26
	s_nop 0
	global_load_lds_dwordx4 v[158:159], off
	v_lshl_add_u64 v[158:159], s[24:25], 0, v[132:133]
	s_add_i32 m0, s26, 0x2000
	s_nop 0
	global_load_lds_dwordx4 v[158:159], off
	v_lshl_add_u64 v[158:159], v[212:213], 0, s[8:9]
	s_mov_b32 m0, s67
	s_nop 0
	global_load_lds_dwordx4 v[158:159], off
	v_lshl_add_u64 v[158:159], v[214:215], 0, s[8:9]
	s_mov_b32 m0, s68
	s_nop 0
	global_load_lds_dwordx4 v[158:159], off
	s_waitcnt vmcnt(8)
	s_waitcnt lgkmcnt(0)
	s_barrier
	s_setprio 1
	s_waitcnt lgkmcnt(0)
	v_mfma_f32_16x16x32_bf16 v[60:63], v[138:141], v[178:181], v[60:63]
	v_mfma_f32_16x16x32_bf16 v[56:59], v[150:153], v[178:181], v[56:59]
	v_mfma_f32_16x16x32_bf16 v[52:55], v[138:141], v[186:189], v[52:55]
	v_mfma_f32_16x16x32_bf16 v[44:47], v[150:153], v[186:189], v[44:47]
	v_mfma_f32_16x16x32_bf16 v[36:39], v[138:141], v[194:197], v[36:39]
	v_mfma_f32_16x16x32_bf16 v[28:31], v[150:153], v[194:197], v[28:31]
	v_mfma_f32_16x16x32_bf16 v[20:23], v[138:141], v[202:205], v[20:23]
	v_mfma_f32_16x16x32_bf16 v[12:15], v[150:153], v[202:205], v[12:15]
	v_mfma_f32_16x16x32_bf16 v[60:63], v[146:149], v[182:185], v[60:63]
	v_mfma_f32_16x16x32_bf16 v[56:59], v[154:157], v[182:185], v[56:59]
	v_mfma_f32_16x16x32_bf16 v[52:55], v[146:149], v[190:193], v[52:55]
	v_mfma_f32_16x16x32_bf16 v[44:47], v[154:157], v[190:193], v[44:47]
	v_mfma_f32_16x16x32_bf16 v[36:39], v[146:149], v[198:201], v[36:39]
	v_mfma_f32_16x16x32_bf16 v[28:31], v[154:157], v[198:201], v[28:31]
	v_mfma_f32_16x16x32_bf16 v[20:23], v[146:149], v[206:209], v[20:23]
	v_mfma_f32_16x16x32_bf16 v[12:15], v[154:157], v[206:209], v[12:15]
	v_mfma_f32_16x16x32_bf16 v[48:51], v[162:165], v[178:181], v[48:51]
	v_mfma_f32_16x16x32_bf16 v[40:43], v[170:173], v[178:181], v[40:43]
	v_mfma_f32_16x16x32_bf16 v[32:35], v[162:165], v[186:189], v[32:35]
	v_mfma_f32_16x16x32_bf16 v[24:27], v[170:173], v[186:189], v[24:27]
	v_mfma_f32_16x16x32_bf16 v[16:19], v[162:165], v[194:197], v[16:19]
	v_mfma_f32_16x16x32_bf16 v[8:11], v[170:173], v[194:197], v[8:11]
	v_mfma_f32_16x16x32_bf16 v[4:7], v[162:165], v[202:205], v[4:7]
	v_mfma_f32_16x16x32_bf16 v[0:3], v[170:173], v[202:205], v[0:3]
	v_mfma_f32_16x16x32_bf16 v[48:51], v[166:169], v[182:185], v[48:51]
	v_mfma_f32_16x16x32_bf16 v[40:43], v[174:177], v[182:185], v[40:43]
	v_mfma_f32_16x16x32_bf16 v[32:35], v[166:169], v[190:193], v[32:35]
	v_mfma_f32_16x16x32_bf16 v[24:27], v[174:177], v[190:193], v[24:27]
	v_mfma_f32_16x16x32_bf16 v[16:19], v[166:169], v[198:201], v[16:19]
	v_mfma_f32_16x16x32_bf16 v[8:11], v[174:177], v[198:201], v[8:11]
	v_mfma_f32_16x16x32_bf16 v[4:7], v[166:169], v[206:209], v[4:7]
	v_mfma_f32_16x16x32_bf16 v[0:3], v[174:177], v[206:209], v[0:3]
	s_setprio 0
	s_barrier
	s_add_i32 s73, s73, 2
	s_add_u32 s58, s58, 0x100
	s_addc_u32 s59, s59, 0
	s_add_u32 s71, s71, 0x100
	s_addc_u32 s72, s72, 0
	s_cmp_gt_u32 s73, 29
	s_cbranch_scc0 .LBB0_674
	s_and_b64 vcc, exec, s[46:47]
	s_cbranch_vccz .LBB0_677
	s_barrier

; #define PG8_STAGE(bufoff, gbase, voff) do { _Pragma("unroll") for (int _i = 0; _i < 2; ++_i) \
;         __builtin_amdgcn_global_load_lds((const unsigned*)((const char*)(gbase) + (voff)[_i]), (PG8_LAS unsigned*)(lds + (bufoff) + ldsw + _i * 8192), 16, 0, 0); } while (0)
; #define PG8_LDA(dst, b, h) do { _Pragma("unroll") for (int m = 0; m < 4; ++m) _Pragma("unroll") for (int k = 0; k < 2; ++k) dst[m][k] = *(const PG8_LAS bf16x8*)(lds + PG8_SA(b, h) + aoff + m * 2048 + k * 1024); } while (0)
; #define PG8_LDB(dst, b, h) do { _Pragma("unroll") for (int n = 0; n < 2; ++n) _Pragma("unroll") for (int k = 0; k < 2; ++k) dst[n][k] = *(const PG8_LAS bf16x8*)(lds + PG8_SB(b, h) + boff + n * 2048 + k * 1024); } while (0)
; #define PG8_MMA(ai, bj, At, Bt) do { __builtin_amdgcn_s_setprio(1); _Pragma("unroll") for (int m = 0; m < 4; ++m) _Pragma("unroll") for (int n = 0; n < 2; ++n) _Pragma("unroll") for (int k = 0; k < 2; ++k) \
;         acc[ai][bj][m][n] = __builtin_amdgcn_mfma_f32_16x16x32_bf16(Bt[n][k], At[m][k], acc[ai][bj][m][n], 0, 0, 0); __builtin_amdgcn_s_setprio(0); } while (0)
; #define PG8_WAIT_V(n) asm volatile("s_waitcnt vmcnt(" #n ")" ::: "memory")
; #define PG8_WAIT_L(n) asm volatile("s_waitcnt lgkmcnt(" #n ")" ::: "memory")
; #define PG8_BAR __builtin_amdgcn_s_barrier()
; template <class Epi, class Sched, bool ALIGN_EPI = false, bool SP2 = false>
; __device__ __forceinline__ void gemm_phase(PG8_LAS unsigned char* lds, const Gemm g, const Sched& S, const Epi& E, const int wid_in) {
;     ...
;         for (int t = 0; t < nt; t += 2) {
;             const bool last = (t == nt - 2);
;             const char* a1 = cA + (size_t)(t + 1) * kstep;
;             const char* a2 = last ? nA : cA + (size_t)(t + 2) * kstep; const char* b2 = last ? nB : cB + (size_t)(t + 2) * kstep;
;             const char* a3 = a2 + kstep; const char* b3 = b2 + kstep;
;             if (last && has_next) S.a_ready(nxt);
;             if constexpr (SP2) {
;             PG8_LDB(B0, 0, 0); PG8_LDB(B1, 0, 1); PG8_SCHED; PG8_LDA(At, 0, 0); PG8_STAGE(PG8_SA(1, 1), a1 + hstep, voffA);
;             PG8_WAIT_V(8); PG8_WAIT_L(0); PG8_BAR; PG8_MMA(0, 0, At, B0); PG8_MMA(0, 1, At, B1); PG8_BAR; PG8_SCHED;
;             PG8_LDA(At, 0, 1); PG8_STAGE(PG8_SB(0, 0), b2, voffB); PG8_STAGE(PG8_SB(0, 1), b2 + hstep, voffB); PG8_STAGE(PG8_SA(0, 0), a2, voffA);
.LBB0_814:
	s_add_u32 s24, s62, 0xfff80080
	s_addc_u32 s25, s63, -1
	s_add_i32 s26, 0, 0x10000
	s_cmp_eq_u32 s39, 28
	s_cselect_b32 s67, s6, s25
	s_cselect_b32 s66, s7, s24
	s_cselect_b32 s65, s14, s35
	s_cselect_b32 s64, s15, s34
	s_add_i32 s27, 0, 0x14000
	v_add_u32_e32 v140, s26, v250
	v_add_u32_e32 v156, s27, v250
	ds_read_b128 v[128:131], v140
	ds_read_b128 v[132:135], v140 offset:1024
	ds_read_b128 v[136:139], v140 offset:2048
	ds_read_b128 v[140:143], v140 offset:3072
	ds_read_b128 v[144:147], v156
	ds_read_b128 v[148:151], v156 offset:1024
	ds_read_b128 v[152:155], v156 offset:2048
	ds_read_b128 v[156:159], v156 offset:3072
	v_lshl_add_u64 v[164:165], s[62:63], 0, v[174:175]
	s_add_i32 m0, s75, 0xc000
	ds_read_b128 v[178:181], v162
	ds_read_b128 v[182:185], v162 offset:1024
	ds_read_b128 v[186:189], v162 offset:2048
	ds_read_b128 v[190:193], v162 offset:3072
	ds_read_b128 v[194:197], v162 offset:4096
	ds_read_b128 v[198:201], v162 offset:5120
	ds_read_b128 v[202:205], v162 offset:6144
	ds_read_b128 v[206:209], v162 offset:7168
	global_load_lds_dwordx4 v[164:165], off
	v_lshl_add_u64 v[164:165], s[62:63], 0, v[176:177]
	s_add_i32 m0, s75, 0xe000
	s_nop 0
	global_load_lds_dwordx4 v[164:165], off
	s_waitcnt vmcnt(8)
	s_waitcnt lgkmcnt(0)
	s_barrier
	s_setprio 1
	s_waitcnt lgkmcnt(0)
	v_mfma_f32_16x16x32_bf16 v[124:127], v[128:131], v[178:181], v[124:127]
	v_mfma_f32_16x16x32_bf16 v[120:123], v[136:139], v[178:181], v[120:123]
	v_mfma_f32_16x16x32_bf16 v[108:111], v[128:131], v[186:189], v[108:111]
	v_mfma_f32_16x16x32_bf16 v[104:107], v[136:139], v[186:189], v[104:107]
	v_mfma_f32_16x16x32_bf16 v[92:95], v[128:131], v[194:197], v[92:95]
	v_mfma_f32_16x16x32_bf16 v[88:91], v[136:139], v[194:197], v[88:91]
	v_mfma_f32_16x16x32_bf16 v[76:79], v[128:131], v[202:205], v[76:79]
	v_mfma_f32_16x16x32_bf16 v[72:75], v[136:139], v[202:205], v[72:75]
	v_mfma_f32_16x16x32_bf16 v[124:127], v[132:135], v[182:185], v[124:127]
	v_mfma_f32_16x16x32_bf16 v[120:123], v[140:143], v[182:185], v[120:123]
	v_mfma_f32_16x16x32_bf16 v[108:111], v[132:135], v[190:193], v[108:111]
	v_mfma_f32_16x16x32_bf16 v[104:107], v[140:143], v[190:193], v[104:107]
	v_mfma_f32_16x16x32_bf16 v[92:95], v[132:135], v[198:201], v[92:95]
	v_mfma_f32_16x16x32_bf16 v[88:91], v[140:143], v[198:201], v[88:91]
	v_mfma_f32_16x16x32_bf16 v[76:79], v[132:135], v[206:209], v[76:79]
	v_mfma_f32_16x16x32_bf16 v[72:75], v[140:143], v[206:209], v[72:75]
	v_mfma_f32_16x16x32_bf16 v[116:119], v[144:147], v[178:181], v[116:119]
	v_mfma_f32_16x16x32_bf16 v[112:115], v[152:155], v[178:181], v[112:115]
	v_mfma_f32_16x16x32_bf16 v[100:103], v[144:147], v[186:189], v[100:103]
	v_mfma_f32_16x16x32_bf16 v[96:99], v[152:155], v[186:189], v[96:99]
	v_mfma_f32_16x16x32_bf16 v[84:87], v[144:147], v[194:197], v[84:87]
	v_mfma_f32_16x16x32_bf16 v[80:83], v[152:155], v[194:197], v[80:83]
	v_mfma_f32_16x16x32_bf16 v[68:71], v[144:147], v[202:205], v[68:71]
	v_mfma_f32_16x16x32_bf16 v[64:67], v[152:155], v[202:205], v[64:67]
	v_mfma_f32_16x16x32_bf16 v[116:119], v[148:151], v[182:185], v[116:119]
	v_mfma_f32_16x16x32_bf16 v[112:115], v[156:159], v[182:185], v[112:115]
	v_mfma_f32_16x16x32_bf16 v[100:103], v[148:151], v[190:193], v[100:103]
	v_mfma_f32_16x16x32_bf16 v[96:99], v[156:159], v[190:193], v[96:99]
	v_mfma_f32_16x16x32_bf16 v[84:87], v[148:151], v[198:201], v[84:87]
	v_mfma_f32_16x16x32_bf16 v[80:83], v[156:159], v[198:201], v[80:83]
	v_mfma_f32_16x16x32_bf16 v[68:71], v[148:151], v[206:209], v[68:71]
	v_mfma_f32_16x16x32_bf16 v[64:67], v[156:159], v[206:209], v[64:67]
	s_setprio 0
	s_barrier
	s_add_i32 s24, s26, s74
	v_lshl_add_u64 v[164:165], s[64:65], 0, v[168:169]
	s_mov_b32 m0, s24
	ds_read_b128 v[178:181], v162 offset:16384
	ds_read_b128 v[182:185], v162 offset:17408
	ds_read_b128 v[186:189], v162 offset:18432
	ds_read_b128 v[190:193], v162 offset:19456
	ds_read_b128 v[194:197], v162 offset:20480
	ds_read_b128 v[198:201], v162 offset:21504
	ds_read_b128 v[202:205], v162 offset:22528
	ds_read_b128 v[206:209], v162 offset:23552
	global_load_lds_dwordx4 v[164:165], off
	s_add_i32 m0, s24, 0x2000
	s_add_u32 s24, s64, 0x80000
	v_lshl_add_u64 v[210:211], s[64:65], 0, v[172:173]
	s_addc_u32 s25, s65, 0
	s_add_i32 s26, s27, s74
	global_load_lds_dwordx4 v[210:211], off
	v_lshl_add_u64 v[212:213], s[24:25], 0, v[168:169]
	s_mov_b32 m0, s26
	v_lshl_add_u64 v[214:215], s[66:67], 0, v[170:171]
	global_load_lds_dwordx4 v[212:213], off
	v_lshl_add_u64 v[212:213], s[24:25], 0, v[172:173]
	s_add_i32 m0, s26, 0x2000
	s_nop 0
	global_load_lds_dwordx4 v[212:213], off
	v_lshl_add_u64 v[212:213], s[66:67], 0, v[166:167]
	s_mov_b32 m0, s75
	s_nop 0
	global_load_lds_dwordx4 v[212:213], off
	s_mov_b32 m0, s76
	s_nop 0
	global_load_lds_dwordx4 v[214:215], off
	s_waitcnt vmcnt(8)
	s_waitcnt lgkmcnt(0)
	s_barrier
; #define PG8_STAGE(bufoff, gbase, voff) do { _Pragma("unroll") for (int _i = 0; _i < 2; ++_i) \
;         __builtin_amdgcn_global_load_lds((const unsigned*)((const char*)(gbase) + (voff)[_i]), (PG8_LAS unsigned*)(lds + (bufoff) + ldsw + _i * 8192), 16, 0, 0); } while (0)
; #define PG8_LDA(dst, b, h) do { _Pragma("unroll") for (int m = 0; m < 4; ++m) _Pragma("unroll") for (int k = 0; k < 2; ++k) dst[m][k] = *(const PG8_LAS bf16x8*)(lds + PG8_SA(b, h) + aoff + m * 2048 + k * 1024); } while (0)
; #define PG8_LDB(dst, b, h) do { _Pragma("unroll") for (int n = 0; n < 2; ++n) _Pragma("unroll") for (int k = 0; k < 2; ++k) dst[n][k] = *(const PG8_LAS bf16x8*)(lds + PG8_SB(b, h) + boff + n * 2048 + k * 1024); } while (0)
; #define PG8_MMA(ai, bj, At, Bt) do { __builtin_amdgcn_s_setprio(1); _Pragma("unroll") for (int m = 0; m < 4; ++m) _Pragma("unroll") for (int n = 0; n < 2; ++n) _Pragma("unroll") for (int k = 0; k < 2; ++k) \
;         acc[ai][bj][m][n] = __builtin_amdgcn_mfma_f32_16x16x32_bf16(Bt[n][k], At[m][k], acc[ai][bj][m][n], 0, 0, 0); __builtin_amdgcn_s_setprio(0); } while (0)
; #define PG8_WAIT_V(n) asm volatile("s_waitcnt vmcnt(" #n ")" ::: "memory")
; #define PG8_WAIT_L(n) asm volatile("s_waitcnt lgkmcnt(" #n ")" ::: "memory")
; #define PG8_BAR __builtin_amdgcn_s_barrier()
; #define PG8_SCHED __builtin_amdgcn_sched_barrier(0)
; template <class Epi, class Sched, bool ALIGN_EPI = false, bool SP2 = false>
; __device__ __forceinline__ void gemm_phase(PG8_LAS unsigned char* lds, const Gemm g, const Sched& S, const Epi& E, const int wid_in) {
;     ...
;             PG8_WAIT_V(8); PG8_WAIT_L(0); PG8_BAR; PG8_MMA(1, 0, At, B0); PG8_MMA(1, 1, At, B1); PG8_BAR; PG8_SCHED;
;             PG8_LDB(B0, 1, 0); PG8_LDB(B1, 1, 1); PG8_SCHED; PG8_LDA(At, 1, 0); PG8_STAGE(PG8_SA(0, 1), a2 + hstep, voffA);
;             PG8_WAIT_V(8); PG8_WAIT_L(0); PG8_BAR; PG8_MMA(0, 0, At, B0); PG8_MMA(0, 1, At, B1); PG8_BAR; PG8_SCHED;
	s_setprio 1
	s_waitcnt lgkmcnt(0)
	v_mfma_f32_16x16x32_bf16 v[60:63], v[128:131], v[178:181], v[60:63]
	v_mfma_f32_16x16x32_bf16 v[56:59], v[136:139], v[178:181], v[56:59]
	v_mfma_f32_16x16x32_bf16 v[44:47], v[128:131], v[186:189], v[44:47]
	v_mfma_f32_16x16x32_bf16 v[40:43], v[136:139], v[186:189], v[40:43]
	v_mfma_f32_16x16x32_bf16 v[28:31], v[128:131], v[194:197], v[28:31]
	v_mfma_f32_16x16x32_bf16 v[24:27], v[136:139], v[194:197], v[24:27]
	v_mfma_f32_16x16x32_bf16 v[12:15], v[128:131], v[202:205], v[12:15]
	v_mfma_f32_16x16x32_bf16 v[8:11], v[136:139], v[202:205], v[8:11]
	v_mfma_f32_16x16x32_bf16 v[60:63], v[132:135], v[182:185], v[60:63]
	v_mfma_f32_16x16x32_bf16 v[56:59], v[140:143], v[182:185], v[56:59]
	v_mfma_f32_16x16x32_bf16 v[44:47], v[132:135], v[190:193], v[44:47]
	v_mfma_f32_16x16x32_bf16 v[40:43], v[140:143], v[190:193], v[40:43]
	v_mfma_f32_16x16x32_bf16 v[28:31], v[132:135], v[198:201], v[28:31]
	v_mfma_f32_16x16x32_bf16 v[24:27], v[140:143], v[198:201], v[24:27]
	v_mfma_f32_16x16x32_bf16 v[12:15], v[132:135], v[206:209], v[12:15]
	v_mfma_f32_16x16x32_bf16 v[8:11], v[140:143], v[206:209], v[8:11]
	v_mfma_f32_16x16x32_bf16 v[52:55], v[144:147], v[178:181], v[52:55]
	v_mfma_f32_16x16x32_bf16 v[48:51], v[152:155], v[178:181], v[48:51]
	v_mfma_f32_16x16x32_bf16 v[36:39], v[144:147], v[186:189], v[36:39]
	v_mfma_f32_16x16x32_bf16 v[32:35], v[152:155], v[186:189], v[32:35]
	v_mfma_f32_16x16x32_bf16 v[20:23], v[144:147], v[194:197], v[20:23]
	v_mfma_f32_16x16x32_bf16 v[16:19], v[152:155], v[194:197], v[16:19]
	v_mfma_f32_16x16x32_bf16 v[4:7], v[144:147], v[202:205], v[4:7]
	v_mfma_f32_16x16x32_bf16 v[0:3], v[152:155], v[202:205], v[0:3]
	v_mfma_f32_16x16x32_bf16 v[52:55], v[148:151], v[182:185], v[52:55]
	v_mfma_f32_16x16x32_bf16 v[48:51], v[156:159], v[182:185], v[48:51]
	v_mfma_f32_16x16x32_bf16 v[36:39], v[148:151], v[190:193], v[36:39]
	v_mfma_f32_16x16x32_bf16 v[32:35], v[156:159], v[190:193], v[32:35]
	v_mfma_f32_16x16x32_bf16 v[20:23], v[148:151], v[198:201], v[20:23]
	v_mfma_f32_16x16x32_bf16 v[16:19], v[156:159], v[198:201], v[16:19]
	v_mfma_f32_16x16x32_bf16 v[4:7], v[148:151], v[206:209], v[4:7]
	v_mfma_f32_16x16x32_bf16 v[0:3], v[156:159], v[206:209], v[0:3]
	s_setprio 0
	s_barrier
	s_add_i32 s26, 0, 0x18000
	s_add_i32 s27, 0, 0x1c000
	v_add_u32_e32 v140, s26, v250
	v_add_u32_e32 v156, s27, v250
	ds_read_b128 v[128:131], v140
	ds_read_b128 v[132:135], v140 offset:1024
	ds_read_b128 v[136:139], v140 offset:2048
	ds_read_b128 v[140:143], v140 offset:3072
	ds_read_b128 v[144:147], v156
	ds_read_b128 v[148:151], v156 offset:1024
	ds_read_b128 v[152:155], v156 offset:2048
	ds_read_b128 v[156:159], v156 offset:3072
	s_add_u32 s24, s66, 0x80000
	s_addc_u32 s25, s67, 0
	s_mov_b32 m0, s77
	v_lshl_add_u64 v[216:217], s[24:25], 0, v[166:167]
	ds_read_b128 v[178:181], v162 offset:32768
	ds_read_b128 v[182:185], v162 offset:33792
	ds_read_b128 v[186:189], v162 offset:34816
	ds_read_b128 v[190:193], v162 offset:35840
	ds_read_b128 v[194:197], v162 offset:36864
	ds_read_b128 v[198:201], v162 offset:37888
	ds_read_b128 v[202:205], v162 offset:38912
	ds_read_b128 v[206:209], v162 offset:39936
	global_load_lds_dwordx4 v[216:217], off
	v_lshl_add_u64 v[216:217], s[24:25], 0, v[170:171]
	s_mov_b32 m0, s78
	s_nop 0
	global_load_lds_dwordx4 v[216:217], off
	s_waitcnt vmcnt(8)
	s_waitcnt lgkmcnt(0)
	s_barrier
	s_setprio 1
	s_waitcnt lgkmcnt(0)
	v_mfma_f32_16x16x32_bf16 v[124:127], v[128:131], v[178:181], v[124:127]
	v_mfma_f32_16x16x32_bf16 v[120:123], v[136:139], v[178:181], v[120:123]
	v_mfma_f32_16x16x32_bf16 v[108:111], v[128:131], v[186:189], v[108:111]
	v_mfma_f32_16x16x32_bf16 v[104:107], v[136:139], v[186:189], v[104:107]
	v_mfma_f32_16x16x32_bf16 v[92:95], v[128:131], v[194:197], v[92:95]
	v_mfma_f32_16x16x32_bf16 v[88:91], v[136:139], v[194:197], v[88:91]
	v_mfma_f32_16x16x32_bf16 v[76:79], v[128:131], v[202:205], v[76:79]
	v_mfma_f32_16x16x32_bf16 v[72:75], v[136:139], v[202:205], v[72:75]
	v_mfma_f32_16x16x32_bf16 v[124:127], v[132:135], v[182:185], v[124:127]
	v_mfma_f32_16x16x32_bf16 v[120:123], v[140:143], v[182:185], v[120:123]
	v_mfma_f32_16x16x32_bf16 v[108:111], v[132:135], v[190:193], v[108:111]
	v_mfma_f32_16x16x32_bf16 v[104:107], v[140:143], v[190:193], v[104:107]
	v_mfma_f32_16x16x32_bf16 v[92:95], v[132:135], v[198:201], v[92:95]
	v_mfma_f32_16x16x32_bf16 v[88:91], v[140:143], v[198:201], v[88:91]
	v_mfma_f32_16x16x32_bf16 v[76:79], v[132:135], v[206:209], v[76:79]
	v_mfma_f32_16x16x32_bf16 v[72:75], v[140:143], v[206:209], v[72:75]
	v_mfma_f32_16x16x32_bf16 v[116:119], v[144:147], v[178:181], v[116:119]
	v_mfma_f32_16x16x32_bf16 v[112:115], v[152:155], v[178:181], v[112:115]
	v_mfma_f32_16x16x32_bf16 v[100:103], v[144:147], v[186:189], v[100:103]
	v_mfma_f32_16x16x32_bf16 v[96:99], v[152:155], v[186:189], v[96:99]
	v_mfma_f32_16x16x32_bf16 v[84:87], v[144:147], v[194:197], v[84:87]
	v_mfma_f32_16x16x32_bf16 v[80:83], v[152:155], v[194:197], v[80:83]
	v_mfma_f32_16x16x32_bf16 v[68:71], v[144:147], v[202:205], v[68:71]
	v_mfma_f32_16x16x32_bf16 v[64:67], v[152:155], v[202:205], v[64:67]
	v_mfma_f32_16x16x32_bf16 v[116:119], v[148:151], v[182:185], v[116:119]
	v_mfma_f32_16x16x32_bf16 v[112:115], v[156:159], v[182:185], v[112:115]
	v_mfma_f32_16x16x32_bf16 v[100:103], v[148:151], v[190:193], v[100:103]
	v_mfma_f32_16x16x32_bf16 v[96:99], v[156:159], v[190:193], v[96:99]
	v_mfma_f32_16x16x32_bf16 v[84:87], v[148:151], v[198:201], v[84:87]
	v_mfma_f32_16x16x32_bf16 v[80:83], v[156:159], v[198:201], v[80:83]
	v_mfma_f32_16x16x32_bf16 v[68:71], v[148:151], v[206:209], v[68:71]
	v_mfma_f32_16x16x32_bf16 v[64:67], v[156:159], v[206:209], v[64:67]
	s_setprio 0
	s_barrier
; #define PG8_STAGE(bufoff, gbase, voff) do { _Pragma("unroll") for (int _i = 0; _i < 2; ++_i) \
;         __builtin_amdgcn_global_load_lds((const unsigned*)((const char*)(gbase) + (voff)[_i]), (PG8_LAS unsigned*)(lds + (bufoff) + ldsw + _i * 8192), 16, 0, 0); } while (0)
; #define PG8_LDA(dst, b, h) do { _Pragma("unroll") for (int m = 0; m < 4; ++m) _Pragma("unroll") for (int k = 0; k < 2; ++k) dst[m][k] = *(const PG8_LAS bf16x8*)(lds + PG8_SA(b, h) + aoff + m * 2048 + k * 1024); } while (0)
; #define PG8_MMA(ai, bj, At, Bt) do { __builtin_amdgcn_s_setprio(1); _Pragma("unroll") for (int m = 0; m < 4; ++m) _Pragma("unroll") for (int n = 0; n < 2; ++n) _Pragma("unroll") for (int k = 0; k < 2; ++k) \
;         acc[ai][bj][m][n] = __builtin_amdgcn_mfma_f32_16x16x32_bf16(Bt[n][k], At[m][k], acc[ai][bj][m][n], 0, 0, 0); __builtin_amdgcn_s_setprio(0); } while (0)
; #define PG8_WAIT_V(n) asm volatile("s_waitcnt vmcnt(" #n ")" ::: "memory")
; #define PG8_WAIT_L(n) asm volatile("s_waitcnt lgkmcnt(" #n ")" ::: "memory")
; #define PG8_BAR __builtin_amdgcn_s_barrier()
; #define PG8_SCHED __builtin_amdgcn_sched_barrier(0)
; template <class Epi, class Sched, bool ALIGN_EPI = false, bool SP2 = false>
; __device__ __forceinline__ void gemm_phase(PG8_LAS unsigned char* lds, const Gemm g, const Sched& S, const Epi& E, const int wid_in) {
;     ...
;             PG8_WAIT_V(8); PG8_WAIT_L(0); PG8_BAR; PG8_MMA(0, 0, At, B0); PG8_MMA(0, 1, At, B1); PG8_BAR; PG8_SCHED;
;             PG8_LDA(At, 1, 1); PG8_STAGE(PG8_SB(1, 0), b3, voffB); PG8_STAGE(PG8_SB(1, 1), b3 + hstep, voffB); PG8_STAGE(PG8_SA(1, 0), a3, voffA);
;             PG8_WAIT_V(8); PG8_WAIT_L(0); PG8_BAR; PG8_MMA(1, 0, At, B0); PG8_MMA(1, 1, At, B1); PG8_BAR; PG8_SCHED;
	s_add_i32 s24, s26, s74
	v_lshl_add_u64 v[164:165], v[164:165], 0, s[8:9]
	s_mov_b32 m0, s24
	ds_read_b128 v[178:181], v162 offset:49152
	ds_read_b128 v[182:185], v162 offset:50176
	ds_read_b128 v[186:189], v162 offset:51200
	ds_read_b128 v[190:193], v162 offset:52224
	ds_read_b128 v[194:197], v162 offset:53248
	ds_read_b128 v[198:201], v162 offset:54272
	ds_read_b128 v[202:205], v162 offset:55296
	ds_read_b128 v[206:209], v162 offset:56320
	global_load_lds_dwordx4 v[164:165], off
	s_add_i32 m0, s24, 0x2000
	s_add_u32 s24, s64, 0x80080
	v_lshl_add_u64 v[164:165], v[210:211], 0, s[8:9]
	s_addc_u32 s25, s65, 0
	s_add_i32 s26, s27, s74
	global_load_lds_dwordx4 v[164:165], off
	v_lshl_add_u64 v[164:165], s[24:25], 0, v[168:169]
	s_mov_b32 m0, s26
	s_nop 0
	global_load_lds_dwordx4 v[164:165], off
	v_lshl_add_u64 v[164:165], s[24:25], 0, v[172:173]
	s_add_i32 m0, s26, 0x2000
	s_nop 0
	global_load_lds_dwordx4 v[164:165], off
	v_lshl_add_u64 v[164:165], v[212:213], 0, s[8:9]
	s_mov_b32 m0, s80
	s_nop 0
	global_load_lds_dwordx4 v[164:165], off
	v_lshl_add_u64 v[164:165], v[214:215], 0, s[8:9]
	s_mov_b32 m0, s81
	s_nop 0
	global_load_lds_dwordx4 v[164:165], off
	s_waitcnt vmcnt(8)
	s_waitcnt lgkmcnt(0)
	s_barrier
	s_setprio 1
	s_waitcnt lgkmcnt(0)
	v_mfma_f32_16x16x32_bf16 v[60:63], v[128:131], v[178:181], v[60:63]
	v_mfma_f32_16x16x32_bf16 v[56:59], v[136:139], v[178:181], v[56:59]
	v_mfma_f32_16x16x32_bf16 v[44:47], v[128:131], v[186:189], v[44:47]
	v_mfma_f32_16x16x32_bf16 v[40:43], v[136:139], v[186:189], v[40:43]
	v_mfma_f32_16x16x32_bf16 v[28:31], v[128:131], v[194:197], v[28:31]
	v_mfma_f32_16x16x32_bf16 v[24:27], v[136:139], v[194:197], v[24:27]
	v_mfma_f32_16x16x32_bf16 v[12:15], v[128:131], v[202:205], v[12:15]
	v_mfma_f32_16x16x32_bf16 v[8:11], v[136:139], v[202:205], v[8:11]
	v_mfma_f32_16x16x32_bf16 v[60:63], v[132:135], v[182:185], v[60:63]
	v_mfma_f32_16x16x32_bf16 v[56:59], v[140:143], v[182:185], v[56:59]
	v_mfma_f32_16x16x32_bf16 v[44:47], v[132:135], v[190:193], v[44:47]
	v_mfma_f32_16x16x32_bf16 v[40:43], v[140:143], v[190:193], v[40:43]
	v_mfma_f32_16x16x32_bf16 v[28:31], v[132:135], v[198:201], v[28:31]
	v_mfma_f32_16x16x32_bf16 v[24:27], v[140:143], v[198:201], v[24:27]
	v_mfma_f32_16x16x32_bf16 v[12:15], v[132:135], v[206:209], v[12:15]
	v_mfma_f32_16x16x32_bf16 v[8:11], v[140:143], v[206:209], v[8:11]
	v_mfma_f32_16x16x32_bf16 v[52:55], v[144:147], v[178:181], v[52:55]
	v_mfma_f32_16x16x32_bf16 v[48:51], v[152:155], v[178:181], v[48:51]
	v_mfma_f32_16x16x32_bf16 v[36:39], v[144:147], v[186:189], v[36:39]
	v_mfma_f32_16x16x32_bf16 v[32:35], v[152:155], v[186:189], v[32:35]
	v_mfma_f32_16x16x32_bf16 v[20:23], v[144:147], v[194:197], v[20:23]
	v_mfma_f32_16x16x32_bf16 v[16:19], v[152:155], v[194:197], v[16:19]
	v_mfma_f32_16x16x32_bf16 v[4:7], v[144:147], v[202:205], v[4:7]
	v_mfma_f32_16x16x32_bf16 v[0:3], v[152:155], v[202:205], v[0:3]
	v_mfma_f32_16x16x32_bf16 v[52:55], v[148:151], v[182:185], v[52:55]
	v_mfma_f32_16x16x32_bf16 v[48:51], v[156:159], v[182:185], v[48:51]
	v_mfma_f32_16x16x32_bf16 v[36:39], v[148:151], v[190:193], v[36:39]
	v_mfma_f32_16x16x32_bf16 v[32:35], v[156:159], v[190:193], v[32:35]
	v_mfma_f32_16x16x32_bf16 v[20:23], v[148:151], v[198:201], v[20:23]
	v_mfma_f32_16x16x32_bf16 v[16:19], v[156:159], v[198:201], v[16:19]
	v_mfma_f32_16x16x32_bf16 v[4:7], v[148:151], v[206:209], v[4:7]
	v_mfma_f32_16x16x32_bf16 v[0:3], v[156:159], v[206:209], v[0:3]
	s_setprio 0
	s_barrier
	s_add_i32 s39, s39, 2
	s_add_u32 s62, s62, 0x100
	s_addc_u32 s63, s63, 0
	s_add_u32 s34, s34, 0x100
	s_addc_u32 s35, s35, 0
	s_cmp_gt_u32 s39, 29
	s_cbranch_scc0 .LBB0_814
	s_and_b64 vcc, exec, s[52:53]
	s_cbranch_vccz .LBB0_817
	s_barrier

; #define PG8_STAGE(bufoff, gbase, voff) do { _Pragma("unroll") for (int _i = 0; _i < 2; ++_i) \
;         __builtin_amdgcn_global_load_lds((const unsigned*)((const char*)(gbase) + (voff)[_i]), (PG8_LAS unsigned*)(lds + (bufoff) + ldsw + _i * 8192), 16, 0, 0); } while (0)
; #define PG8_LDA(dst, b, h) do { _Pragma("unroll") for (int m = 0; m < 4; ++m) _Pragma("unroll") for (int k = 0; k < 2; ++k) dst[m][k] = *(const PG8_LAS bf16x8*)(lds + PG8_SA(b, h) + aoff + m * 2048 + k * 1024); } while (0)
; #define PG8_LDB(dst, b, h) do { _Pragma("unroll") for (int n = 0; n < 2; ++n) _Pragma("unroll") for (int k = 0; k < 2; ++k) dst[n][k] = *(const PG8_LAS bf16x8*)(lds + PG8_SB(b, h) + boff + n * 2048 + k * 1024); } while (0)
; #define PG8_MMA(ai, bj, At, Bt) do { __builtin_amdgcn_s_setprio(1); _Pragma("unroll") for (int m = 0; m < 4; ++m) _Pragma("unroll") for (int n = 0; n < 2; ++n) _Pragma("unroll") for (int k = 0; k < 2; ++k) \
;         acc[ai][bj][m][n] = __builtin_amdgcn_mfma_f32_16x16x32_bf16(Bt[n][k], At[m][k], acc[ai][bj][m][n], 0, 0, 0); __builtin_amdgcn_s_setprio(0); } while (0)
; #define PG8_WAIT_V(n) asm volatile("s_waitcnt vmcnt(" #n ")" ::: "memory")
; #define PG8_WAIT_L(n) asm volatile("s_waitcnt lgkmcnt(" #n ")" ::: "memory")
; #define PG8_BAR __builtin_amdgcn_s_barrier()
; template <class Epi, class Sched, bool ALIGN_EPI = false, bool SP2 = false>
; __device__ __forceinline__ void gemm_phase(PG8_LAS unsigned char* lds, const Gemm g, const Sched& S, const Epi& E, const int wid_in) {
;     ...
;         for (int t = 0; t < nt; t += 2) {
;             const bool last = (t == nt - 2);
;             const char* a1 = cA + (size_t)(t + 1) * kstep;
;             const char* a2 = last ? nA : cA + (size_t)(t + 2) * kstep; const char* b2 = last ? nB : cB + (size_t)(t + 2) * kstep;
;             const char* a3 = a2 + kstep; const char* b3 = b2 + kstep;
;             if (last && has_next) S.a_ready(nxt);
;             if constexpr (SP2) {
;             PG8_LDB(B0, 0, 0); PG8_LDB(B1, 0, 1); PG8_SCHED; PG8_LDA(At, 0, 0); PG8_STAGE(PG8_SA(1, 1), a1 + hstep, voffA);
;             PG8_WAIT_V(8); PG8_WAIT_L(0); PG8_BAR; PG8_MMA(0, 0, At, B0); PG8_MMA(0, 1, At, B1); PG8_BAR; PG8_SCHED;
;             PG8_LDA(At, 0, 1); PG8_STAGE(PG8_SB(0, 0), b2, voffB); PG8_STAGE(PG8_SB(0, 1), b2 + hstep, voffB); PG8_STAGE(PG8_SA(0, 0), a2, voffA);
.LBB0_1009:
	s_add_u32 s42, s54, 0x100
	s_addc_u32 s43, s55, 0
	s_add_i32 s24, 0, 0x10000
	s_cmpk_eq_i32 s18, 0x54
	s_cselect_b32 s59, s51, s43
	s_cselect_b32 s58, s50, s42
	v_add_u32_e32 v146, s24, v149
	s_cselect_b32 s57, s53, s15
	s_cselect_b32 s56, s52, s14
	s_add_i32 s26, 0, 0x14000
	ds_read_b128 v[138:141], v146
	ds_read_b128 v[142:145], v146 offset:1024
	ds_read_b128 v[152:155], v146 offset:2048
	ds_read_b128 v[156:159], v146 offset:3072
	v_add_u32_e32 v146, s26, v149
	ds_read_b128 v[162:165], v146
	ds_read_b128 v[166:169], v146 offset:1024
	ds_read_b128 v[170:173], v146 offset:2048
	ds_read_b128 v[174:177], v146 offset:3072
	v_lshl_add_u64 v[146:147], s[54:55], 0, v[134:135]
	s_add_i32 m0, s63, 0xc000
	ds_read_b128 v[178:181], v151
	ds_read_b128 v[182:185], v151 offset:1024
	ds_read_b128 v[186:189], v151 offset:2048
	ds_read_b128 v[190:193], v151 offset:3072
	ds_read_b128 v[194:197], v151 offset:4096
	ds_read_b128 v[198:201], v151 offset:5120
	ds_read_b128 v[202:205], v151 offset:6144
	ds_read_b128 v[206:209], v151 offset:7168
	global_load_lds_dwordx4 v[146:147], off
	v_lshl_add_u64 v[146:147], s[54:55], 0, v[136:137]
	s_add_i32 m0, s63, 0xe000
	s_nop 0
	global_load_lds_dwordx4 v[146:147], off
	s_waitcnt vmcnt(8)
	s_waitcnt lgkmcnt(0)
	s_barrier
	s_setprio 1
	s_waitcnt lgkmcnt(0)
	v_mfma_f32_16x16x32_bf16 v[124:127], v[138:141], v[178:181], v[124:127]
	v_mfma_f32_16x16x32_bf16 v[120:123], v[152:155], v[178:181], v[120:123]
	v_mfma_f32_16x16x32_bf16 v[108:111], v[138:141], v[186:189], v[108:111]
	v_mfma_f32_16x16x32_bf16 v[104:107], v[152:155], v[186:189], v[104:107]
	v_mfma_f32_16x16x32_bf16 v[92:95], v[138:141], v[194:197], v[92:95]
	v_mfma_f32_16x16x32_bf16 v[88:91], v[152:155], v[194:197], v[88:91]
	v_mfma_f32_16x16x32_bf16 v[76:79], v[138:141], v[202:205], v[76:79]
	v_mfma_f32_16x16x32_bf16 v[72:75], v[152:155], v[202:205], v[72:75]
	v_mfma_f32_16x16x32_bf16 v[124:127], v[142:145], v[182:185], v[124:127]
	v_mfma_f32_16x16x32_bf16 v[120:123], v[156:159], v[182:185], v[120:123]
	v_mfma_f32_16x16x32_bf16 v[108:111], v[142:145], v[190:193], v[108:111]
	v_mfma_f32_16x16x32_bf16 v[104:107], v[156:159], v[190:193], v[104:107]
	v_mfma_f32_16x16x32_bf16 v[92:95], v[142:145], v[198:201], v[92:95]
	v_mfma_f32_16x16x32_bf16 v[88:91], v[156:159], v[198:201], v[88:91]
	v_mfma_f32_16x16x32_bf16 v[76:79], v[142:145], v[206:209], v[76:79]
	v_mfma_f32_16x16x32_bf16 v[72:75], v[156:159], v[206:209], v[72:75]
	v_mfma_f32_16x16x32_bf16 v[116:119], v[162:165], v[178:181], v[116:119]
	v_mfma_f32_16x16x32_bf16 v[112:115], v[170:173], v[178:181], v[112:115]
	v_mfma_f32_16x16x32_bf16 v[100:103], v[162:165], v[186:189], v[100:103]
	v_mfma_f32_16x16x32_bf16 v[96:99], v[170:173], v[186:189], v[96:99]
	v_mfma_f32_16x16x32_bf16 v[84:87], v[162:165], v[194:197], v[84:87]
	v_mfma_f32_16x16x32_bf16 v[80:83], v[170:173], v[194:197], v[80:83]
	v_mfma_f32_16x16x32_bf16 v[68:71], v[162:165], v[202:205], v[68:71]
	v_mfma_f32_16x16x32_bf16 v[64:67], v[170:173], v[202:205], v[64:67]
	v_mfma_f32_16x16x32_bf16 v[116:119], v[166:169], v[182:185], v[116:119]
	v_mfma_f32_16x16x32_bf16 v[112:115], v[174:177], v[182:185], v[112:115]
	v_mfma_f32_16x16x32_bf16 v[100:103], v[166:169], v[190:193], v[100:103]
	v_mfma_f32_16x16x32_bf16 v[96:99], v[174:177], v[190:193], v[96:99]
	v_mfma_f32_16x16x32_bf16 v[84:87], v[166:169], v[198:201], v[84:87]
	v_mfma_f32_16x16x32_bf16 v[80:83], v[174:177], v[198:201], v[80:83]
	v_mfma_f32_16x16x32_bf16 v[68:71], v[166:169], v[206:209], v[68:71]
	v_mfma_f32_16x16x32_bf16 v[64:67], v[174:177], v[206:209], v[64:67]
	s_setprio 0
	s_barrier
	s_add_i32 s24, s24, s62
	v_lshl_add_u64 v[146:147], s[56:57], 0, v[160:161]
	s_mov_b32 m0, s24
	ds_read_b128 v[178:181], v151 offset:16384
	ds_read_b128 v[182:185], v151 offset:17408
	ds_read_b128 v[186:189], v151 offset:18432
	ds_read_b128 v[190:193], v151 offset:19456
	ds_read_b128 v[194:197], v151 offset:20480
	ds_read_b128 v[198:201], v151 offset:21504
	ds_read_b128 v[202:205], v151 offset:22528
	ds_read_b128 v[206:209], v151 offset:23552
	global_load_lds_dwordx4 v[146:147], off
	s_add_i32 m0, s24, 0x2000
	s_add_u32 s24, s56, 0x160000
	v_lshl_add_u64 v[210:211], s[56:57], 0, v[132:133]
	s_addc_u32 s25, s57, 0
	s_add_i32 s26, s26, s62
	global_load_lds_dwordx4 v[210:211], off
	v_lshl_add_u64 v[212:213], s[24:25], 0, v[160:161]
	s_mov_b32 m0, s26
	v_lshl_add_u64 v[214:215], s[58:59], 0, v[130:131]
	global_load_lds_dwordx4 v[212:213], off
	v_lshl_add_u64 v[212:213], s[24:25], 0, v[132:133]
	s_add_i32 m0, s26, 0x2000
	s_nop 0
	global_load_lds_dwordx4 v[212:213], off
	v_lshl_add_u64 v[212:213], s[58:59], 0, v[128:129]
	s_mov_b32 m0, s63
	s_nop 0
	global_load_lds_dwordx4 v[212:213], off
	s_mov_b32 m0, s64
	s_nop 0
	global_load_lds_dwordx4 v[214:215], off
	s_waitcnt vmcnt(8)
	s_waitcnt lgkmcnt(0)
	s_barrier
; #define PG8_STAGE(bufoff, gbase, voff) do { _Pragma("unroll") for (int _i = 0; _i < 2; ++_i) \
;         __builtin_amdgcn_global_load_lds((const unsigned*)((const char*)(gbase) + (voff)[_i]), (PG8_LAS unsigned*)(lds + (bufoff) + ldsw + _i * 8192), 16, 0, 0); } while (0)
; #define PG8_LDA(dst, b, h) do { _Pragma("unroll") for (int m = 0; m < 4; ++m) _Pragma("unroll") for (int k = 0; k < 2; ++k) dst[m][k] = *(const PG8_LAS bf16x8*)(lds + PG8_SA(b, h) + aoff + m * 2048 + k * 1024); } while (0)
; #define PG8_LDB(dst, b, h) do { _Pragma("unroll") for (int n = 0; n < 2; ++n) _Pragma("unroll") for (int k = 0; k < 2; ++k) dst[n][k] = *(const PG8_LAS bf16x8*)(lds + PG8_SB(b, h) + boff + n * 2048 + k * 1024); } while (0)
; #define PG8_MMA(ai, bj, At, Bt) do { __builtin_amdgcn_s_setprio(1); _Pragma("unroll") for (int m = 0; m < 4; ++m) _Pragma("unroll") for (int n = 0; n < 2; ++n) _Pragma("unroll") for (int k = 0; k < 2; ++k) \
;         acc[ai][bj][m][n] = __builtin_amdgcn_mfma_f32_16x16x32_bf16(Bt[n][k], At[m][k], acc[ai][bj][m][n], 0, 0, 0); __builtin_amdgcn_s_setprio(0); } while (0)
; #define PG8_WAIT_V(n) asm volatile("s_waitcnt vmcnt(" #n ")" ::: "memory")
; #define PG8_WAIT_L(n) asm volatile("s_waitcnt lgkmcnt(" #n ")" ::: "memory")
; #define PG8_BAR __builtin_amdgcn_s_barrier()
; #define PG8_SCHED __builtin_amdgcn_sched_barrier(0)
; template <class Epi, class Sched, bool ALIGN_EPI = false, bool SP2 = false>
; __device__ __forceinline__ void gemm_phase(PG8_LAS unsigned char* lds, const Gemm g, const Sched& S, const Epi& E, const int wid_in) {
;     ...
;             PG8_WAIT_V(8); PG8_WAIT_L(0); PG8_BAR; PG8_MMA(1, 0, At, B0); PG8_MMA(1, 1, At, B1); PG8_BAR; PG8_SCHED;
;             PG8_LDB(B0, 1, 0); PG8_LDB(B1, 1, 1); PG8_SCHED; PG8_LDA(At, 1, 0); PG8_STAGE(PG8_SA(0, 1), a2 + hstep, voffA);
;             PG8_WAIT_V(8); PG8_WAIT_L(0); PG8_BAR; PG8_MMA(0, 0, At, B0); PG8_MMA(0, 1, At, B1); PG8_BAR; PG8_SCHED;
	s_setprio 1
	s_waitcnt lgkmcnt(0)
	v_mfma_f32_16x16x32_bf16 v[60:63], v[138:141], v[178:181], v[60:63]
	v_mfma_f32_16x16x32_bf16 v[56:59], v[152:155], v[178:181], v[56:59]
	v_mfma_f32_16x16x32_bf16 v[44:47], v[138:141], v[186:189], v[44:47]
	v_mfma_f32_16x16x32_bf16 v[40:43], v[152:155], v[186:189], v[40:43]
	v_mfma_f32_16x16x32_bf16 v[28:31], v[138:141], v[194:197], v[28:31]
	v_mfma_f32_16x16x32_bf16 v[24:27], v[152:155], v[194:197], v[24:27]
	v_mfma_f32_16x16x32_bf16 v[12:15], v[138:141], v[202:205], v[12:15]
	v_mfma_f32_16x16x32_bf16 v[8:11], v[152:155], v[202:205], v[8:11]
	v_mfma_f32_16x16x32_bf16 v[60:63], v[142:145], v[182:185], v[60:63]
	v_mfma_f32_16x16x32_bf16 v[56:59], v[156:159], v[182:185], v[56:59]
	v_mfma_f32_16x16x32_bf16 v[44:47], v[142:145], v[190:193], v[44:47]
	v_mfma_f32_16x16x32_bf16 v[40:43], v[156:159], v[190:193], v[40:43]
	v_mfma_f32_16x16x32_bf16 v[28:31], v[142:145], v[198:201], v[28:31]
	v_mfma_f32_16x16x32_bf16 v[24:27], v[156:159], v[198:201], v[24:27]
	v_mfma_f32_16x16x32_bf16 v[12:15], v[142:145], v[206:209], v[12:15]
	v_mfma_f32_16x16x32_bf16 v[8:11], v[156:159], v[206:209], v[8:11]
	v_mfma_f32_16x16x32_bf16 v[52:55], v[162:165], v[178:181], v[52:55]
	v_mfma_f32_16x16x32_bf16 v[48:51], v[170:173], v[178:181], v[48:51]
	v_mfma_f32_16x16x32_bf16 v[36:39], v[162:165], v[186:189], v[36:39]
	v_mfma_f32_16x16x32_bf16 v[32:35], v[170:173], v[186:189], v[32:35]
	v_mfma_f32_16x16x32_bf16 v[20:23], v[162:165], v[194:197], v[20:23]
	v_mfma_f32_16x16x32_bf16 v[16:19], v[170:173], v[194:197], v[16:19]
	v_mfma_f32_16x16x32_bf16 v[4:7], v[162:165], v[202:205], v[4:7]
	v_mfma_f32_16x16x32_bf16 v[0:3], v[170:173], v[202:205], v[0:3]
	v_mfma_f32_16x16x32_bf16 v[52:55], v[166:169], v[182:185], v[52:55]
	v_mfma_f32_16x16x32_bf16 v[48:51], v[174:177], v[182:185], v[48:51]
	v_mfma_f32_16x16x32_bf16 v[36:39], v[166:169], v[190:193], v[36:39]
	v_mfma_f32_16x16x32_bf16 v[32:35], v[174:177], v[190:193], v[32:35]
	v_mfma_f32_16x16x32_bf16 v[20:23], v[166:169], v[198:201], v[20:23]
	v_mfma_f32_16x16x32_bf16 v[16:19], v[174:177], v[198:201], v[16:19]
	v_mfma_f32_16x16x32_bf16 v[4:7], v[166:169], v[206:209], v[4:7]
	v_mfma_f32_16x16x32_bf16 v[0:3], v[174:177], v[206:209], v[0:3]
	s_setprio 0
	s_barrier
	s_add_i32 s26, 0, 0x18000
	s_add_i32 s27, 0, 0x1c000
	v_add_u32_e32 v156, s26, v149
	v_add_u32_e32 v174, s27, v149
	ds_read_b128 v[138:141], v156
	ds_read_b128 v[142:145], v156 offset:1024
	ds_read_b128 v[152:155], v156 offset:2048
	ds_read_b128 v[156:159], v156 offset:3072
	ds_read_b128 v[162:165], v174
	ds_read_b128 v[166:169], v174 offset:1024
	ds_read_b128 v[170:173], v174 offset:2048
	ds_read_b128 v[174:177], v174 offset:3072
	s_add_u32 s24, s58, 0x160000
	s_addc_u32 s25, s59, 0
	s_mov_b32 m0, s65
	v_lshl_add_u64 v[216:217], s[24:25], 0, v[128:129]
	ds_read_b128 v[178:181], v151 offset:32768
	ds_read_b128 v[182:185], v151 offset:33792
	ds_read_b128 v[186:189], v151 offset:34816
	ds_read_b128 v[190:193], v151 offset:35840
	ds_read_b128 v[194:197], v151 offset:36864
	ds_read_b128 v[198:201], v151 offset:37888
	ds_read_b128 v[202:205], v151 offset:38912
	ds_read_b128 v[206:209], v151 offset:39936
	global_load_lds_dwordx4 v[216:217], off
	v_lshl_add_u64 v[216:217], s[24:25], 0, v[130:131]
	s_mov_b32 m0, s66
	s_nop 0
	global_load_lds_dwordx4 v[216:217], off
	s_waitcnt vmcnt(8)
	s_waitcnt lgkmcnt(0)
	s_barrier
	s_setprio 1
	s_waitcnt lgkmcnt(0)
	v_mfma_f32_16x16x32_bf16 v[124:127], v[138:141], v[178:181], v[124:127]
	v_mfma_f32_16x16x32_bf16 v[120:123], v[152:155], v[178:181], v[120:123]
	v_mfma_f32_16x16x32_bf16 v[108:111], v[138:141], v[186:189], v[108:111]
	v_mfma_f32_16x16x32_bf16 v[104:107], v[152:155], v[186:189], v[104:107]
	v_mfma_f32_16x16x32_bf16 v[92:95], v[138:141], v[194:197], v[92:95]
	v_mfma_f32_16x16x32_bf16 v[88:91], v[152:155], v[194:197], v[88:91]
	v_mfma_f32_16x16x32_bf16 v[76:79], v[138:141], v[202:205], v[76:79]
	v_mfma_f32_16x16x32_bf16 v[72:75], v[152:155], v[202:205], v[72:75]
	v_mfma_f32_16x16x32_bf16 v[124:127], v[142:145], v[182:185], v[124:127]
	v_mfma_f32_16x16x32_bf16 v[120:123], v[156:159], v[182:185], v[120:123]
	v_mfma_f32_16x16x32_bf16 v[108:111], v[142:145], v[190:193], v[108:111]
	v_mfma_f32_16x16x32_bf16 v[104:107], v[156:159], v[190:193], v[104:107]
	v_mfma_f32_16x16x32_bf16 v[92:95], v[142:145], v[198:201], v[92:95]
	v_mfma_f32_16x16x32_bf16 v[88:91], v[156:159], v[198:201], v[88:91]
	v_mfma_f32_16x16x32_bf16 v[76:79], v[142:145], v[206:209], v[76:79]
	v_mfma_f32_16x16x32_bf16 v[72:75], v[156:159], v[206:209], v[72:75]
	v_mfma_f32_16x16x32_bf16 v[116:119], v[162:165], v[178:181], v[116:119]
	v_mfma_f32_16x16x32_bf16 v[112:115], v[170:173], v[178:181], v[112:115]
	v_mfma_f32_16x16x32_bf16 v[100:103], v[162:165], v[186:189], v[100:103]
	v_mfma_f32_16x16x32_bf16 v[96:99], v[170:173], v[186:189], v[96:99]
	v_mfma_f32_16x16x32_bf16 v[84:87], v[162:165], v[194:197], v[84:87]
	v_mfma_f32_16x16x32_bf16 v[80:83], v[170:173], v[194:197], v[80:83]
	v_mfma_f32_16x16x32_bf16 v[68:71], v[162:165], v[202:205], v[68:71]
	v_mfma_f32_16x16x32_bf16 v[64:67], v[170:173], v[202:205], v[64:67]
	v_mfma_f32_16x16x32_bf16 v[116:119], v[166:169], v[182:185], v[116:119]
	v_mfma_f32_16x16x32_bf16 v[112:115], v[174:177], v[182:185], v[112:115]
	v_mfma_f32_16x16x32_bf16 v[100:103], v[166:169], v[190:193], v[100:103]
	v_mfma_f32_16x16x32_bf16 v[96:99], v[174:177], v[190:193], v[96:99]
	v_mfma_f32_16x16x32_bf16 v[84:87], v[166:169], v[198:201], v[84:87]
	v_mfma_f32_16x16x32_bf16 v[80:83], v[174:177], v[198:201], v[80:83]
	v_mfma_f32_16x16x32_bf16 v[68:71], v[166:169], v[206:209], v[68:71]
	v_mfma_f32_16x16x32_bf16 v[64:67], v[174:177], v[206:209], v[64:67]
	s_setprio 0
	s_barrier
; #define PG8_STAGE(bufoff, gbase, voff) do { _Pragma("unroll") for (int _i = 0; _i < 2; ++_i) \
;         __builtin_amdgcn_global_load_lds((const unsigned*)((const char*)(gbase) + (voff)[_i]), (PG8_LAS unsigned*)(lds + (bufoff) + ldsw + _i * 8192), 16, 0, 0); } while (0)
; #define PG8_LDA(dst, b, h) do { _Pragma("unroll") for (int m = 0; m < 4; ++m) _Pragma("unroll") for (int k = 0; k < 2; ++k) dst[m][k] = *(const PG8_LAS bf16x8*)(lds + PG8_SA(b, h) + aoff + m * 2048 + k * 1024); } while (0)
; #define PG8_MMA(ai, bj, At, Bt) do { __builtin_amdgcn_s_setprio(1); _Pragma("unroll") for (int m = 0; m < 4; ++m) _Pragma("unroll") for (int n = 0; n < 2; ++n) _Pragma("unroll") for (int k = 0; k < 2; ++k) \
;         acc[ai][bj][m][n] = __builtin_amdgcn_mfma_f32_16x16x32_bf16(Bt[n][k], At[m][k], acc[ai][bj][m][n], 0, 0, 0); __builtin_amdgcn_s_setprio(0); } while (0)
; #define PG8_WAIT_V(n) asm volatile("s_waitcnt vmcnt(" #n ")" ::: "memory")
; #define PG8_WAIT_L(n) asm volatile("s_waitcnt lgkmcnt(" #n ")" ::: "memory")
; #define PG8_BAR __builtin_amdgcn_s_barrier()
; #define PG8_SCHED __builtin_amdgcn_sched_barrier(0)
; template <class Epi, class Sched, bool ALIGN_EPI = false, bool SP2 = false>
; __device__ __forceinline__ void gemm_phase(PG8_LAS unsigned char* lds, const Gemm g, const Sched& S, const Epi& E, const int wid_in) {
;     ...
;         for (int t = 0; t < nt; t += 2) {
;     ...
;             PG8_LDA(At, 1, 1); PG8_STAGE(PG8_SB(1, 0), b3, voffB); PG8_STAGE(PG8_SB(1, 1), b3 + hstep, voffB); PG8_STAGE(PG8_SA(1, 0), a3, voffA);
;             PG8_WAIT_V(8); PG8_WAIT_L(0); PG8_BAR; PG8_MMA(1, 0, At, B0); PG8_MMA(1, 1, At, B1); PG8_BAR; PG8_SCHED;
	s_add_i32 s24, s26, s62
	v_lshl_add_u64 v[146:147], v[146:147], 0, s[8:9]
	s_mov_b32 m0, s24
	ds_read_b128 v[178:181], v151 offset:49152
	ds_read_b128 v[182:185], v151 offset:50176
	ds_read_b128 v[186:189], v151 offset:51200
	ds_read_b128 v[190:193], v151 offset:52224
	ds_read_b128 v[194:197], v151 offset:53248
	ds_read_b128 v[198:201], v151 offset:54272
	ds_read_b128 v[202:205], v151 offset:55296
	ds_read_b128 v[206:209], v151 offset:56320
	global_load_lds_dwordx4 v[146:147], off
	s_add_i32 m0, s24, 0x2000
	s_add_u32 s24, s56, 0x160080
	v_lshl_add_u64 v[146:147], v[210:211], 0, s[8:9]
	s_addc_u32 s25, s57, 0
	s_add_i32 s26, s27, s62
	global_load_lds_dwordx4 v[146:147], off
	v_lshl_add_u64 v[146:147], s[24:25], 0, v[160:161]
	s_mov_b32 m0, s26
	s_nop 0
	global_load_lds_dwordx4 v[146:147], off
	v_lshl_add_u64 v[146:147], s[24:25], 0, v[132:133]
	s_add_i32 m0, s26, 0x2000
	s_nop 0
	global_load_lds_dwordx4 v[146:147], off
	v_lshl_add_u64 v[146:147], v[212:213], 0, s[8:9]
	s_mov_b32 m0, s68
	s_nop 0
	global_load_lds_dwordx4 v[146:147], off
	v_lshl_add_u64 v[146:147], v[214:215], 0, s[8:9]
	s_mov_b32 m0, s69
	s_nop 0
	global_load_lds_dwordx4 v[146:147], off
	s_waitcnt vmcnt(8)
	s_waitcnt lgkmcnt(0)
	s_barrier
	s_setprio 1
	s_waitcnt lgkmcnt(0)
	v_mfma_f32_16x16x32_bf16 v[60:63], v[138:141], v[178:181], v[60:63]
	v_mfma_f32_16x16x32_bf16 v[56:59], v[152:155], v[178:181], v[56:59]
	v_mfma_f32_16x16x32_bf16 v[44:47], v[138:141], v[186:189], v[44:47]
	v_mfma_f32_16x16x32_bf16 v[40:43], v[152:155], v[186:189], v[40:43]
	v_mfma_f32_16x16x32_bf16 v[28:31], v[138:141], v[194:197], v[28:31]
	v_mfma_f32_16x16x32_bf16 v[24:27], v[152:155], v[194:197], v[24:27]
	v_mfma_f32_16x16x32_bf16 v[12:15], v[138:141], v[202:205], v[12:15]
	v_mfma_f32_16x16x32_bf16 v[8:11], v[152:155], v[202:205], v[8:11]
	v_mfma_f32_16x16x32_bf16 v[60:63], v[142:145], v[182:185], v[60:63]
	v_mfma_f32_16x16x32_bf16 v[56:59], v[156:159], v[182:185], v[56:59]
	v_mfma_f32_16x16x32_bf16 v[44:47], v[142:145], v[190:193], v[44:47]
	v_mfma_f32_16x16x32_bf16 v[40:43], v[156:159], v[190:193], v[40:43]
	v_mfma_f32_16x16x32_bf16 v[28:31], v[142:145], v[198:201], v[28:31]
	v_mfma_f32_16x16x32_bf16 v[24:27], v[156:159], v[198:201], v[24:27]
	v_mfma_f32_16x16x32_bf16 v[12:15], v[142:145], v[206:209], v[12:15]
	v_mfma_f32_16x16x32_bf16 v[8:11], v[156:159], v[206:209], v[8:11]
	v_mfma_f32_16x16x32_bf16 v[52:55], v[162:165], v[178:181], v[52:55]
	v_mfma_f32_16x16x32_bf16 v[48:51], v[170:173], v[178:181], v[48:51]
	v_mfma_f32_16x16x32_bf16 v[36:39], v[162:165], v[186:189], v[36:39]
	v_mfma_f32_16x16x32_bf16 v[32:35], v[170:173], v[186:189], v[32:35]
	v_mfma_f32_16x16x32_bf16 v[20:23], v[162:165], v[194:197], v[20:23]
	v_mfma_f32_16x16x32_bf16 v[16:19], v[170:173], v[194:197], v[16:19]
	v_mfma_f32_16x16x32_bf16 v[4:7], v[162:165], v[202:205], v[4:7]
	v_mfma_f32_16x16x32_bf16 v[0:3], v[170:173], v[202:205], v[0:3]
	v_mfma_f32_16x16x32_bf16 v[52:55], v[166:169], v[182:185], v[52:55]
	v_mfma_f32_16x16x32_bf16 v[48:51], v[174:177], v[182:185], v[48:51]
	v_mfma_f32_16x16x32_bf16 v[36:39], v[166:169], v[190:193], v[36:39]
	v_mfma_f32_16x16x32_bf16 v[32:35], v[174:177], v[190:193], v[32:35]
	v_mfma_f32_16x16x32_bf16 v[20:23], v[166:169], v[198:201], v[20:23]
	v_mfma_f32_16x16x32_bf16 v[16:19], v[174:177], v[198:201], v[16:19]
	v_mfma_f32_16x16x32_bf16 v[4:7], v[166:169], v[206:209], v[4:7]
	v_mfma_f32_16x16x32_bf16 v[0:3], v[174:177], v[206:209], v[0:3]
	s_setprio 0
	s_barrier
	s_add_i32 s18, s18, 2
	s_add_u32 s14, s14, 0x100
	s_addc_u32 s15, s15, 0
	s_cmpk_gt_u32 s18, 0x55
	s_mov_b64 s[54:55], s[42:43]
	s_cbranch_scc0 .LBB0_1009
	s_and_b64 vcc, exec, s[48:49]
	s_cbranch_vccz .LBB0_1012
	s_barrier
